# SwiGLU GEMMs (P2,P9): waves 4-7 run their tile epilogue before the last post-MFMA barrier so both wave groups' epilogues overlap instead of serialising behind the barrier; on top of v9
# speedup vs baseline: 1.0089x; 1.0018x over previous
; #define PG8_STAGE(bufoff, gbase, voff) do { _Pragma("unroll") for (int _i = 0; _i < 2; ++_i) \
;         __builtin_amdgcn_global_load_lds((const unsigned*)((const char*)(gbase) + (voff)[_i]), (LAS unsigned*)(lds + (bufoff) + ldsw + _i * 8192), 16, 0, 0); } while (0)
; #define PG8_LDA(dst, b, h) do { _Pragma("unroll") for (int m = 0; m < 4; ++m) _Pragma("unroll") for (int k = 0; k < 2; ++k) dst[m][k] = *(const LAS bf16x8*)(lds + PG8_SA(b, h) + aoff + m * 2048 + k * 1024); } while (0)
; #define PG8_LDB(dst, b, h) do { _Pragma("unroll") for (int n = 0; n < 2; ++n) _Pragma("unroll") for (int k = 0; k < 2; ++k) dst[n][k] = *(const LAS bf16x8*)(lds + PG8_SB(b, h) + boff + n * 2048 + k * 1024); } while (0)
; #define PG8_MMA(ai, bj, At, Bt) do { __builtin_amdgcn_s_setprio(1); _Pragma("unroll") for (int m = 0; m < 4; ++m) _Pragma("unroll") for (int n = 0; n < 2; ++n) _Pragma("unroll") for (int k = 0; k < 2; ++k) \
;         acc[ai][bj][m][n] = __builtin_amdgcn_mfma_f32_16x16x32_bf16(Bt[n][k], At[m][k], acc[ai][bj][m][n], 0, 0, 0); __builtin_amdgcn_s_setprio(0); } while (0)
; #define PG8_WAIT_V(n) asm volatile("s_waitcnt vmcnt(" #n ")" ::: "memory")
; #define PG8_WAIT_L(n) asm volatile("s_waitcnt lgkmcnt(" #n ")" ::: "memory")
; template <class Epi, class Sched>
; __device__ __forceinline__ void gemm_phase(LAS unsigned char* lds, const Gemm g, const Sched& S, const Epi& E) {
;     ...
;         for (int t = 0; t < nt; t += 2) {
;             const bool last = (t == nt - 2);
;             const char* a1 = cA + (size_t)(t + 1) * kstep;
;             const char* a2 = last ? nA : cA + (size_t)(t + 2) * kstep; const char* b2 = last ? nB : cB + (size_t)(t + 2) * kstep;
;             const char* a3 = a2 + kstep; const char* b3 = b2 + kstep;
;             PG8_LDB(B0, 0, 0); PG8_SCHED; PG8_LDA(At, 0, 0); PG8_STAGE(PG8_SA(1, 1), a1 + hstep, voffA);
;             PG8_WAIT_L(8); PG8_BAR; PG8_WAIT_L(0); PG8_MMA(0, 0, At, B0); PG8_BAR; PG8_SCHED;
;             PG8_LDB(B1, 0, 1); PG8_STAGE(PG8_SB(0, 0), b2, voffB);
;             PG8_BAR; PG8_WAIT_L(0); PG8_MMA(0, 1, At, B1); PG8_BAR;
;             PG8_LDA(At, 0, 1); PG8_STAGE(PG8_SA(0, 0), a2, voffA);
;             PG8_BAR; PG8_WAIT_L(0); PG8_MMA(1, 0, At, B0); PG8_BAR; PG8_SCHED;
;             PG8_STAGE(PG8_SB(0, 1), b2 + hstep, voffB);
;             PG8_WAIT_V(6); PG8_BAR; PG8_MMA(1, 1, At, B1); PG8_BAR;
.LBB0_235:
	ds_read_b128 v[150:153], v147
	ds_read_b128 v[154:157], v147 offset:1024
	ds_read_b128 v[158:161], v147 offset:2048
	ds_read_b128 v[162:165], v147 offset:3072
	s_add_u32 s16, s14, 0xfffc0080
	s_addc_u32 s17, s15, -1
	s_cmp_eq_u32 s48, 12
	s_cselect_b32 s23, s7, s17
	s_cselect_b32 s22, s44, s16
	s_cselect_b32 s19, s5, s47
	s_cselect_b32 s18, s45, s46
	s_add_i32 m0, s13, 0xc000
	ds_read_b128 v[166:169], v148
	ds_read_b128 v[170:173], v148 offset:1024
	ds_read_b128 v[174:177], v148 offset:2048
	ds_read_b128 v[178:181], v148 offset:3072
	ds_read_b128 v[182:185], v148 offset:4096
	ds_read_b128 v[186:189], v148 offset:5120
	ds_read_b128 v[190:193], v148 offset:6144
	ds_read_b128 v[194:197], v148 offset:7168
	global_load_lds_dwordx4 v136, s[14:15]
	s_add_i32 m0, s13, 0xe000
	s_nop 0
	global_load_lds_dwordx4 v138, s[14:15]
	s_waitcnt lgkmcnt(8)
	s_waitcnt vmcnt(10)
	s_barrier
	s_waitcnt lgkmcnt(0)
	s_setprio 1
	s_waitcnt lgkmcnt(0)
	v_mfma_f32_16x16x32_bf16 v[124:127], v[150:153], v[166:169], v[124:127]
	v_mfma_f32_16x16x32_bf16 v[116:119], v[158:161], v[166:169], v[116:119]
	v_mfma_f32_16x16x32_bf16 v[108:111], v[150:153], v[174:177], v[108:111]
	v_mfma_f32_16x16x32_bf16 v[100:103], v[158:161], v[174:177], v[100:103]
	v_mfma_f32_16x16x32_bf16 v[92:95], v[150:153], v[182:185], v[92:95]
	v_mfma_f32_16x16x32_bf16 v[84:87], v[158:161], v[182:185], v[84:87]
	v_mfma_f32_16x16x32_bf16 v[76:79], v[150:153], v[190:193], v[76:79]
	v_mfma_f32_16x16x32_bf16 v[68:71], v[158:161], v[190:193], v[68:71]
	v_mfma_f32_16x16x32_bf16 v[124:127], v[154:157], v[170:173], v[124:127]
	v_mfma_f32_16x16x32_bf16 v[116:119], v[162:165], v[170:173], v[116:119]
	v_mfma_f32_16x16x32_bf16 v[108:111], v[154:157], v[178:181], v[108:111]
	v_mfma_f32_16x16x32_bf16 v[100:103], v[162:165], v[178:181], v[100:103]
	v_mfma_f32_16x16x32_bf16 v[92:95], v[154:157], v[186:189], v[92:95]
	v_mfma_f32_16x16x32_bf16 v[84:87], v[162:165], v[186:189], v[84:87]
	v_mfma_f32_16x16x32_bf16 v[76:79], v[154:157], v[194:197], v[76:79]
	v_mfma_f32_16x16x32_bf16 v[68:71], v[162:165], v[194:197], v[68:71]
	s_setprio 0
	s_barrier
	s_add_i32 s16, s40, s25
	s_mov_b32 m0, s16
	ds_read_b128 v[202:205], v149
	ds_read_b128 v[206:209], v149 offset:1024
	ds_read_b128 v[210:213], v149 offset:2048
	ds_read_b128 v[214:217], v149 offset:3072
	global_load_lds_dwordx4 v132, s[18:19]
	s_add_i32 m0, s16, 0x2000
	s_nop 0
	global_load_lds_dwordx4 v128, s[18:19]
	s_waitcnt vmcnt(10)
	s_barrier
	s_waitcnt lgkmcnt(0)
	s_setprio 1
	s_waitcnt lgkmcnt(0)
	v_mfma_f32_16x16x32_bf16 v[120:123], v[202:205], v[166:169], v[120:123]
	v_mfma_f32_16x16x32_bf16 v[112:115], v[210:213], v[166:169], v[112:115]
	v_mfma_f32_16x16x32_bf16 v[104:107], v[202:205], v[174:177], v[104:107]
	v_mfma_f32_16x16x32_bf16 v[96:99], v[210:213], v[174:177], v[96:99]
	v_mfma_f32_16x16x32_bf16 v[88:91], v[202:205], v[182:185], v[88:91]
	v_mfma_f32_16x16x32_bf16 v[80:83], v[210:213], v[182:185], v[80:83]
	v_mfma_f32_16x16x32_bf16 v[72:75], v[202:205], v[190:193], v[72:75]
	v_mfma_f32_16x16x32_bf16 v[64:67], v[210:213], v[190:193], v[64:67]
	v_mfma_f32_16x16x32_bf16 v[120:123], v[206:209], v[170:173], v[120:123]
	v_mfma_f32_16x16x32_bf16 v[112:115], v[214:217], v[170:173], v[112:115]
	v_mfma_f32_16x16x32_bf16 v[104:107], v[206:209], v[178:181], v[104:107]
	v_mfma_f32_16x16x32_bf16 v[96:99], v[214:217], v[178:181], v[96:99]
	v_mfma_f32_16x16x32_bf16 v[88:91], v[206:209], v[186:189], v[88:91]
	v_mfma_f32_16x16x32_bf16 v[80:83], v[214:217], v[186:189], v[80:83]
	v_mfma_f32_16x16x32_bf16 v[72:75], v[206:209], v[194:197], v[72:75]
	v_mfma_f32_16x16x32_bf16 v[64:67], v[214:217], v[194:197], v[64:67]
	s_setprio 0
	s_mov_b32 m0, s13
	s_barrier
	ds_read_b128 v[166:169], v148 offset:16384
	ds_read_b128 v[170:173], v148 offset:17408
	ds_read_b128 v[174:177], v148 offset:18432
	ds_read_b128 v[178:181], v148 offset:19456
	ds_read_b128 v[182:185], v148 offset:20480
	ds_read_b128 v[186:189], v148 offset:21504
	ds_read_b128 v[190:193], v148 offset:22528
	ds_read_b128 v[194:197], v148 offset:23552
	global_load_lds_dwordx4 v134, s[22:23]
	s_mov_b32 m0, s28
	s_nop 0
	global_load_lds_dwordx4 v130, s[22:23]
	s_barrier
	s_waitcnt lgkmcnt(0)
	s_setprio 1
	s_waitcnt lgkmcnt(0)
	v_mfma_f32_16x16x32_bf16 v[60:63], v[150:153], v[166:169], v[60:63]
	v_mfma_f32_16x16x32_bf16 v[56:59], v[158:161], v[166:169], v[56:59]
	v_mfma_f32_16x16x32_bf16 v[44:47], v[150:153], v[174:177], v[44:47]
	v_mfma_f32_16x16x32_bf16 v[40:43], v[158:161], v[174:177], v[40:43]
	v_mfma_f32_16x16x32_bf16 v[28:31], v[150:153], v[182:185], v[28:31]
	v_mfma_f32_16x16x32_bf16 v[24:27], v[158:161], v[182:185], v[24:27]
	v_mfma_f32_16x16x32_bf16 v[12:15], v[150:153], v[190:193], v[12:15]
	v_mfma_f32_16x16x32_bf16 v[8:11], v[158:161], v[190:193], v[8:11]
	v_mfma_f32_16x16x32_bf16 v[60:63], v[154:157], v[170:173], v[60:63]
	v_mfma_f32_16x16x32_bf16 v[56:59], v[162:165], v[170:173], v[56:59]
	v_mfma_f32_16x16x32_bf16 v[44:47], v[154:157], v[178:181], v[44:47]
	v_mfma_f32_16x16x32_bf16 v[40:43], v[162:165], v[178:181], v[40:43]
	v_mfma_f32_16x16x32_bf16 v[28:31], v[154:157], v[186:189], v[28:31]
	v_mfma_f32_16x16x32_bf16 v[24:27], v[162:165], v[186:189], v[24:27]
	v_mfma_f32_16x16x32_bf16 v[12:15], v[154:157], v[194:197], v[12:15]
	v_mfma_f32_16x16x32_bf16 v[8:11], v[162:165], v[194:197], v[8:11]
	s_setprio 0
	s_barrier
	s_add_u32 s16, s18, 0x40000
	s_addc_u32 s17, s19, 0
	s_add_i32 s20, s41, s25
	s_mov_b32 m0, s20
	s_nop 0
	global_load_lds_dwordx4 v132, s[16:17]
	s_add_i32 m0, s20, 0x2000
	s_nop 0
	global_load_lds_dwordx4 v128, s[16:17]
	s_add_u32 s16, s22, 0x40000
	s_addc_u32 s17, s23, 0
	s_mov_b32 m0, s29
	s_nop 0
	global_load_lds_dwordx4 v134, s[16:17]
	s_mov_b32 m0, s33
	s_nop 0
	global_load_lds_dwordx4 v130, s[16:17]
	s_waitcnt vmcnt(12)
	s_barrier
; #define PG8_STAGE(bufoff, gbase, voff) do { _Pragma("unroll") for (int _i = 0; _i < 2; ++_i) \
;         __builtin_amdgcn_global_load_lds((const unsigned*)((const char*)(gbase) + (voff)[_i]), (LAS unsigned*)(lds + (bufoff) + ldsw + _i * 8192), 16, 0, 0); } while (0)
; #define PG8_LDA(dst, b, h) do { _Pragma("unroll") for (int m = 0; m < 4; ++m) _Pragma("unroll") for (int k = 0; k < 2; ++k) dst[m][k] = *(const LAS bf16x8*)(lds + PG8_SA(b, h) + aoff + m * 2048 + k * 1024); } while (0)
; #define PG8_LDB(dst, b, h) do { _Pragma("unroll") for (int n = 0; n < 2; ++n) _Pragma("unroll") for (int k = 0; k < 2; ++k) dst[n][k] = *(const LAS bf16x8*)(lds + PG8_SB(b, h) + boff + n * 2048 + k * 1024); } while (0)
; #define PG8_MMA(ai, bj, At, Bt) do { __builtin_amdgcn_s_setprio(1); _Pragma("unroll") for (int m = 0; m < 4; ++m) _Pragma("unroll") for (int n = 0; n < 2; ++n) _Pragma("unroll") for (int k = 0; k < 2; ++k) \
;         acc[ai][bj][m][n] = __builtin_amdgcn_mfma_f32_16x16x32_bf16(Bt[n][k], At[m][k], acc[ai][bj][m][n], 0, 0, 0); __builtin_amdgcn_s_setprio(0); } while (0)
; #define PG8_WAIT_V(n) asm volatile("s_waitcnt vmcnt(" #n ")" ::: "memory")
; #define PG8_WAIT_L(n) asm volatile("s_waitcnt lgkmcnt(" #n ")" ::: "memory")
; #define PG8_BAR __builtin_amdgcn_s_barrier()
; #define PG8_SCHED __builtin_amdgcn_sched_barrier(0)
; template <class Epi, class Sched>
; __device__ __forceinline__ void gemm_phase(LAS unsigned char* lds, const Gemm g, const Sched& S, const Epi& E) {
;     ...
;             PG8_WAIT_V(6); PG8_BAR; PG8_MMA(1, 1, At, B1); PG8_BAR;
;             PG8_LDB(B0, 1, 0); PG8_SCHED; PG8_LDA(At, 1, 0); PG8_STAGE(PG8_SA(0, 1), a2 + hstep, voffA);
;             PG8_WAIT_L(8); PG8_BAR; PG8_WAIT_L(0); PG8_MMA(0, 0, At, B0); PG8_BAR; PG8_SCHED;
;             PG8_LDB(B1, 1, 1); PG8_STAGE(PG8_SB(1, 0), b3, voffB);
;             PG8_BAR; PG8_WAIT_L(0); PG8_MMA(0, 1, At, B1); PG8_BAR;
;             PG8_LDA(At, 1, 1); PG8_STAGE(PG8_SA(1, 0), a3, voffA);
;             PG8_BAR; PG8_WAIT_L(0); PG8_MMA(1, 0, At, B0); PG8_BAR; PG8_SCHED;
	s_setprio 1
	v_mfma_f32_16x16x32_bf16 v[52:55], v[202:205], v[166:169], v[52:55]
	v_mfma_f32_16x16x32_bf16 v[48:51], v[210:213], v[166:169], v[48:51]
	v_mfma_f32_16x16x32_bf16 v[36:39], v[202:205], v[174:177], v[36:39]
	v_mfma_f32_16x16x32_bf16 v[32:35], v[210:213], v[174:177], v[32:35]
	v_mfma_f32_16x16x32_bf16 v[20:23], v[202:205], v[182:185], v[20:23]
	v_mfma_f32_16x16x32_bf16 v[16:19], v[210:213], v[182:185], v[16:19]
	v_mfma_f32_16x16x32_bf16 v[4:7], v[202:205], v[190:193], v[4:7]
	v_mfma_f32_16x16x32_bf16 v[0:3], v[210:213], v[190:193], v[0:3]
	v_mfma_f32_16x16x32_bf16 v[52:55], v[206:209], v[170:173], v[52:55]
	v_mfma_f32_16x16x32_bf16 v[48:51], v[214:217], v[170:173], v[48:51]
	v_mfma_f32_16x16x32_bf16 v[36:39], v[206:209], v[178:181], v[36:39]
	v_mfma_f32_16x16x32_bf16 v[32:35], v[214:217], v[178:181], v[32:35]
	v_mfma_f32_16x16x32_bf16 v[20:23], v[206:209], v[186:189], v[20:23]
	v_mfma_f32_16x16x32_bf16 v[16:19], v[214:217], v[186:189], v[16:19]
	v_mfma_f32_16x16x32_bf16 v[4:7], v[206:209], v[194:197], v[4:7]
	v_mfma_f32_16x16x32_bf16 v[0:3], v[214:217], v[194:197], v[0:3]
	s_setprio 0
	s_add_i32 s20, 0, 0x18000
	v_add_u32_e32 v162, s20, v146
	s_barrier
	ds_read_b128 v[150:153], v162
	ds_read_b128 v[154:157], v162 offset:1024
	ds_read_b128 v[158:161], v162 offset:2048
	ds_read_b128 v[162:165], v162 offset:3072
	ds_read_b128 v[166:169], v148 offset:32768
	ds_read_b128 v[170:173], v148 offset:33792
	ds_read_b128 v[174:177], v148 offset:34816
	ds_read_b128 v[178:181], v148 offset:35840
	ds_read_b128 v[182:185], v148 offset:36864
	ds_read_b128 v[186:189], v148 offset:37888
	ds_read_b128 v[190:193], v148 offset:38912
	ds_read_b128 v[194:197], v148 offset:39936
	s_waitcnt lgkmcnt(8)
	s_waitcnt vmcnt(10)
	s_barrier
	s_waitcnt lgkmcnt(0)
	s_setprio 1
	s_waitcnt lgkmcnt(0)
	v_mfma_f32_16x16x32_bf16 v[124:127], v[150:153], v[166:169], v[124:127]
	v_mfma_f32_16x16x32_bf16 v[116:119], v[158:161], v[166:169], v[116:119]
	v_mfma_f32_16x16x32_bf16 v[108:111], v[150:153], v[174:177], v[108:111]
	v_mfma_f32_16x16x32_bf16 v[100:103], v[158:161], v[174:177], v[100:103]
	v_mfma_f32_16x16x32_bf16 v[92:95], v[150:153], v[182:185], v[92:95]
	v_mfma_f32_16x16x32_bf16 v[84:87], v[158:161], v[182:185], v[84:87]
	v_mfma_f32_16x16x32_bf16 v[76:79], v[150:153], v[190:193], v[76:79]
	v_mfma_f32_16x16x32_bf16 v[68:71], v[158:161], v[190:193], v[68:71]
	v_mfma_f32_16x16x32_bf16 v[124:127], v[154:157], v[170:173], v[124:127]
	v_mfma_f32_16x16x32_bf16 v[116:119], v[162:165], v[170:173], v[116:119]
	v_mfma_f32_16x16x32_bf16 v[108:111], v[154:157], v[178:181], v[108:111]
	v_mfma_f32_16x16x32_bf16 v[100:103], v[162:165], v[178:181], v[100:103]
	v_mfma_f32_16x16x32_bf16 v[92:95], v[154:157], v[186:189], v[92:95]
	v_mfma_f32_16x16x32_bf16 v[84:87], v[162:165], v[186:189], v[84:87]
	v_mfma_f32_16x16x32_bf16 v[76:79], v[154:157], v[194:197], v[76:79]
	v_mfma_f32_16x16x32_bf16 v[68:71], v[162:165], v[194:197], v[68:71]
	s_setprio 0
	s_barrier
	s_add_i32 s21, 0, 0x1c000
	s_add_i32 s16, s20, s25
	v_add_u32_e32 v214, s21, v146
	s_add_u32 s0, s18, 0x80
	s_addc_u32 s1, s19, 0
	s_mov_b32 m0, s16
	ds_read_b128 v[202:205], v214
	ds_read_b128 v[206:209], v214 offset:1024
	ds_read_b128 v[210:213], v214 offset:2048
	ds_read_b128 v[214:217], v214 offset:3072
	global_load_lds_dwordx4 v132, s[0:1]
	s_add_i32 m0, s16, 0x2000
	s_nop 0
	global_load_lds_dwordx4 v128, s[0:1]
	s_waitcnt vmcnt(10)
	s_barrier
	s_waitcnt lgkmcnt(0)
	s_setprio 1
	s_waitcnt lgkmcnt(0)
	v_mfma_f32_16x16x32_bf16 v[120:123], v[202:205], v[166:169], v[120:123]
	v_mfma_f32_16x16x32_bf16 v[112:115], v[210:213], v[166:169], v[112:115]
	v_mfma_f32_16x16x32_bf16 v[104:107], v[202:205], v[174:177], v[104:107]
	v_mfma_f32_16x16x32_bf16 v[96:99], v[210:213], v[174:177], v[96:99]
	v_mfma_f32_16x16x32_bf16 v[88:91], v[202:205], v[182:185], v[88:91]
	v_mfma_f32_16x16x32_bf16 v[80:83], v[210:213], v[182:185], v[80:83]
	v_mfma_f32_16x16x32_bf16 v[72:75], v[202:205], v[190:193], v[72:75]
	v_mfma_f32_16x16x32_bf16 v[64:67], v[210:213], v[190:193], v[64:67]
	v_mfma_f32_16x16x32_bf16 v[120:123], v[206:209], v[170:173], v[120:123]
	v_mfma_f32_16x16x32_bf16 v[112:115], v[214:217], v[170:173], v[112:115]
	v_mfma_f32_16x16x32_bf16 v[104:107], v[206:209], v[178:181], v[104:107]
	v_mfma_f32_16x16x32_bf16 v[96:99], v[214:217], v[178:181], v[96:99]
	v_mfma_f32_16x16x32_bf16 v[88:91], v[206:209], v[186:189], v[88:91]
	v_mfma_f32_16x16x32_bf16 v[80:83], v[214:217], v[186:189], v[80:83]
	v_mfma_f32_16x16x32_bf16 v[72:75], v[206:209], v[194:197], v[72:75]
	v_mfma_f32_16x16x32_bf16 v[64:67], v[214:217], v[194:197], v[64:67]
	s_setprio 0
	s_mov_b32 m0, s36
	s_add_u32 s0, s22, 0x80
	s_addc_u32 s1, s23, 0
	s_barrier
	ds_read_b128 v[166:169], v148 offset:49152
	ds_read_b128 v[170:173], v148 offset:50176
	ds_read_b128 v[174:177], v148 offset:51200
	ds_read_b128 v[178:181], v148 offset:52224
	ds_read_b128 v[182:185], v148 offset:53248
	ds_read_b128 v[186:189], v148 offset:54272
	ds_read_b128 v[190:193], v148 offset:55296
	ds_read_b128 v[194:197], v148 offset:56320
	global_load_lds_dwordx4 v134, s[0:1]
	s_mov_b32 m0, s37
	s_nop 0
	global_load_lds_dwordx4 v130, s[0:1]
	s_barrier
; __device__ __forceinline__ unsigned cvt_pk_bf16(float lo, float hi) { unsigned r; asm volatile("v_cvt_pk_bf16_f32 %0, %1, %2" : "=v"(r) : "v"(lo), "v"(hi)); return r; }
; __device__ __forceinline__ float silu_f(float a) { return a * __builtin_amdgcn_rcpf(1.0f + __expf(-a)); }
; #define PG8_MMA(ai, bj, At, Bt) do { __builtin_amdgcn_s_setprio(1); _Pragma("unroll") for (int m = 0; m < 4; ++m) _Pragma("unroll") for (int n = 0; n < 2; ++n) _Pragma("unroll") for (int k = 0; k < 2; ++k) \
;         acc[ai][bj][m][n] = __builtin_amdgcn_mfma_f32_16x16x32_bf16(Bt[n][k], At[m][k], acc[ai][bj][m][n], 0, 0, 0); __builtin_amdgcn_s_setprio(0); } while (0)
; #define PG8_WAIT_V(n) asm volatile("s_waitcnt vmcnt(" #n ")" ::: "memory")
; #define PG8_BAR __builtin_amdgcn_s_barrier()
; template <class Epi, class Sched>
; __device__ __forceinline__ void gemm_phase(LAS unsigned char* lds, const Gemm g, const Sched& S, const Epi& E) {
;     ...
;             PG8_WAIT_V(6); PG8_BAR; PG8_MMA(1, 1, At, B1); PG8_BAR;
;         }
;         E(acc, cur, wr, wc, fr, fq);
;     __device__ __forceinline__ void operator()(const AccT& acc, const Unit& u, int wr, int wc, int fr, int fq) const {
;     ...
;         const int row0 = u.pm * 256 + wr * 64 + fr, hc0 = u.pn * 128 + wc * 32 + 8 * fq;
; #pragma unroll
;         for (int ai = 0; ai < 2; ++ai)
; #pragma unroll
;             for (int m = 0; m < 4; ++m) {
;                 const f32x4 a0 = acc[ai][0][m][0], a1 = acc[ai][0][m][1], b0 = acc[ai][1][m][0], b1 = acc[ai][1][m][1];
;                 u32x4 w;
;                 w.x = cvt_pk_bf16(silu_f(a0[0]) * b0[0], silu_f(a0[1]) * b0[1]); w.y = cvt_pk_bf16(silu_f(a0[2]) * b0[2], silu_f(a0[3]) * b0[3]);
;                 w.z = cvt_pk_bf16(silu_f(a1[0]) * b1[0], silu_f(a1[1]) * b1[1]); w.w = cvt_pk_bf16(silu_f(a1[2]) * b1[2], silu_f(a1[3]) * b1[3]);
;                 *(u32x4*)(H + (size_t)(row0 + ai * 128 + m * 16) * DFF + hc0) = w;
	s_waitcnt lgkmcnt(0)
	s_setprio 1
	s_waitcnt lgkmcnt(0)
	v_mfma_f32_16x16x32_bf16 v[60:63], v[150:153], v[166:169], v[60:63]
	v_mfma_f32_16x16x32_bf16 v[56:59], v[158:161], v[166:169], v[56:59]
	v_mfma_f32_16x16x32_bf16 v[44:47], v[150:153], v[174:177], v[44:47]
	v_mfma_f32_16x16x32_bf16 v[40:43], v[158:161], v[174:177], v[40:43]
	v_mfma_f32_16x16x32_bf16 v[28:31], v[150:153], v[182:185], v[28:31]
	v_mfma_f32_16x16x32_bf16 v[24:27], v[158:161], v[182:185], v[24:27]
	v_mfma_f32_16x16x32_bf16 v[12:15], v[150:153], v[190:193], v[12:15]
	v_mfma_f32_16x16x32_bf16 v[8:11], v[158:161], v[190:193], v[8:11]
	v_mfma_f32_16x16x32_bf16 v[60:63], v[154:157], v[170:173], v[60:63]
	v_mfma_f32_16x16x32_bf16 v[56:59], v[162:165], v[170:173], v[56:59]
	v_mfma_f32_16x16x32_bf16 v[44:47], v[154:157], v[178:181], v[44:47]
	v_mfma_f32_16x16x32_bf16 v[40:43], v[162:165], v[178:181], v[40:43]
	v_mfma_f32_16x16x32_bf16 v[28:31], v[154:157], v[186:189], v[28:31]
	v_mfma_f32_16x16x32_bf16 v[24:27], v[162:165], v[186:189], v[24:27]
	v_mfma_f32_16x16x32_bf16 v[12:15], v[154:157], v[194:197], v[12:15]
	v_mfma_f32_16x16x32_bf16 v[8:11], v[162:165], v[194:197], v[8:11]
	s_setprio 0
	s_barrier
	s_add_u32 s16, s18, 0x40080
	s_addc_u32 s17, s19, 0
	s_add_i32 s18, s21, s25
	s_mov_b32 m0, s18
	s_nop 0
	global_load_lds_dwordx4 v132, s[16:17]
	s_add_i32 m0, s18, 0x2000
	s_nop 0
	global_load_lds_dwordx4 v128, s[16:17]
	s_waitcnt vmcnt(10)
	s_barrier
	s_setprio 1
	v_mfma_f32_16x16x32_bf16 v[52:55], v[202:205], v[166:169], v[52:55]
	v_mfma_f32_16x16x32_bf16 v[48:51], v[210:213], v[166:169], v[48:51]
	v_mfma_f32_16x16x32_bf16 v[36:39], v[202:205], v[174:177], v[36:39]
	v_mfma_f32_16x16x32_bf16 v[32:35], v[210:213], v[174:177], v[32:35]
	v_mfma_f32_16x16x32_bf16 v[20:23], v[202:205], v[182:185], v[20:23]
	v_mfma_f32_16x16x32_bf16 v[16:19], v[210:213], v[182:185], v[16:19]
	v_mfma_f32_16x16x32_bf16 v[4:7], v[202:205], v[190:193], v[4:7]
	v_mfma_f32_16x16x32_bf16 v[0:3], v[210:213], v[190:193], v[0:3]
	v_mfma_f32_16x16x32_bf16 v[52:55], v[206:209], v[170:173], v[52:55]
	v_mfma_f32_16x16x32_bf16 v[48:51], v[214:217], v[170:173], v[48:51]
	v_mfma_f32_16x16x32_bf16 v[36:39], v[206:209], v[178:181], v[36:39]
	v_mfma_f32_16x16x32_bf16 v[32:35], v[214:217], v[178:181], v[32:35]
	v_mfma_f32_16x16x32_bf16 v[20:23], v[206:209], v[186:189], v[20:23]
	v_mfma_f32_16x16x32_bf16 v[16:19], v[214:217], v[186:189], v[16:19]
	v_mfma_f32_16x16x32_bf16 v[4:7], v[206:209], v[194:197], v[4:7]
	v_mfma_f32_16x16x32_bf16 v[0:3], v[214:217], v[194:197], v[0:3]
	s_setprio 0
	s_add_i32 s48, s48, 2
	s_add_u32 s14, s14, 0x100
	s_addc_u32 s15, s15, 0
	s_add_u32 s46, s46, 0x100
	s_addc_u32 s47, s47, 0
	s_cmp_gt_u32 s48, 13
	s_cbranch_scc1 .Lconc_last_g0
	s_barrier
	s_branch .LBB0_235
.Lconc_last_g0:
	v_readfirstlane_b32 s5, v200
	s_nop 3
	s_cmp_gt_u32 s5, 0xff
	s_cbranch_scc1 .Lconc_epi1_g0
	s_barrier
	v_mul_f32_e32 v152, 0xbfb8aa3b, v124
	v_mov_b32_e32 v151, v145
	v_mov_b32_e32 v150, v144
	s_lshl_b32 s5, s12, 8
	v_exp_f32_e32 v153, v152
	v_mul_f32_e32 v152, 0xbfb8aa3b, v125
	s_add_i32 s5, s5, s34
	v_exp_f32_e32 v154, v152
	v_add_u32_e32 v150, s5, v150
	s_lshl_b32 s5, s43, 7
	s_or_b32 s5, s5, s35
	v_lshl_add_u32 v152, v151, 3, s5
	v_add_f32_e32 v151, 1.0, v153
	v_rcp_f32_e32 v151, v151
	v_add_f32_e32 v153, 1.0, v154
	v_rcp_f32_e32 v154, v153
	v_ashrrev_i32_e32 v153, 31, v152
	v_mul_f32_e32 v124, v124, v151
	v_mul_f32_e32 v120, v124, v120
	v_mul_f32_e32 v124, v125, v154
	v_mul_f32_e32 v125, 0xbfb8aa3b, v126
	v_exp_f32_e32 v125, v125
	v_mul_f32_e32 v151, 0xbfb8aa3b, v127
	v_exp_f32_e32 v151, v151
	v_mul_f32_e32 v121, v124, v121
	v_add_f32_e32 v124, 1.0, v125
	v_rcp_f32_e32 v124, v124
	v_add_f32_e32 v125, 1.0, v151
	v_rcp_f32_e32 v125, v125
	v_cvt_pk_bf16_f32 v120, v120, v121
	v_mul_f32_e32 v121, v126, v124
	v_mul_f32_e32 v124, 0xbfb8aa3b, v116
	v_mul_f32_e32 v121, v121, v122
	v_mul_f32_e32 v122, v127, v125
	v_exp_f32_e32 v124, v124
	v_mul_f32_e32 v125, 0xbfb8aa3b, v117
	v_exp_f32_e32 v125, v125
	v_mul_f32_e32 v122, v122, v123
	v_add_f32_e32 v123, 1.0, v124
	v_rcp_f32_e32 v123, v123
	v_add_f32_e32 v124, 1.0, v125
	v_rcp_f32_e32 v124, v124
	v_cvt_pk_bf16_f32 v121, v121, v122
	v_mul_f32_e32 v116, v116, v123
	v_mul_f32_e32 v112, v116, v112
	v_mul_f32_e32 v116, v117, v124
	v_mul_f32_e32 v117, 0xbfb8aa3b, v118
	v_exp_f32_e32 v117, v117
	v_mul_f32_e32 v122, 0xbfb8aa3b, v119
	v_exp_f32_e32 v122, v122
	v_mul_f32_e32 v113, v116, v113
	v_add_f32_e32 v116, 1.0, v117
	v_rcp_f32_e32 v116, v116
	v_add_f32_e32 v117, 1.0, v122
	v_rcp_f32_e32 v117, v117
	v_cvt_pk_bf16_f32 v122, v112, v113
	v_mul_f32_e32 v112, v118, v116
	v_mul_f32_e32 v118, 0xbfb8aa3b, v108
	v_mul_f32_e32 v113, v119, v117
	v_exp_f32_e32 v118, v118
	v_mul_f32_e32 v119, 0xbfb8aa3b, v109
	v_exp_f32_e32 v119, v119
	v_mul_f32_e32 v112, v112, v114
	v_add_f32_e32 v118, 1.0, v118
	v_rcp_f32_e32 v118, v118
	v_add_f32_e32 v119, 1.0, v119
	v_rcp_f32_e32 v119, v119
	v_mul_f32_e32 v113, v113, v115
	v_cvt_pk_bf16_f32 v123, v112, v113
	v_mov_b64_e32 v[112:113], s[82:83]
	v_mad_i64_i32 v[116:117], s[14:15], v150, s42, v[112:113]
	v_lshlrev_b64 v[114:115], 1, v[152:153]
	v_mul_f32_e32 v108, v108, v118
	v_lshl_add_u64 v[116:117], v[116:117], 0, v[114:115]
	v_mul_f32_e32 v104, v108, v104
	v_mul_f32_e32 v108, v109, v119
	v_mul_f32_e32 v109, 0xbfb8aa3b, v110
	global_store_dwordx4 v[116:117], v[120:123], off
	v_exp_f32_e32 v109, v109
	v_mul_f32_e32 v116, 0xbfb8aa3b, v111
	v_exp_f32_e32 v116, v116
	v_mul_f32_e32 v105, v108, v105
	v_add_f32_e32 v108, 1.0, v109
	v_rcp_f32_e32 v108, v108
	v_add_f32_e32 v109, 1.0, v116
	v_rcp_f32_e32 v109, v109
	v_cvt_pk_bf16_f32 v104, v104, v105
; __device__ __forceinline__ unsigned cvt_pk_bf16(float lo, float hi) { unsigned r; asm volatile("v_cvt_pk_bf16_f32 %0, %1, %2" : "=v"(r) : "v"(lo), "v"(hi)); return r; }
; __device__ __forceinline__ float silu_f(float a) { return a * __builtin_amdgcn_rcpf(1.0f + __expf(-a)); }
;     __device__ __forceinline__ void operator()(const AccT& acc, const Unit& u, int wr, int wc, int fr, int fq) const {
;     ...
;         const int row0 = u.pm * 256 + wr * 64 + fr, hc0 = u.pn * 128 + wc * 32 + 8 * fq;
; #pragma unroll
;         for (int ai = 0; ai < 2; ++ai)
; #pragma unroll
;             for (int m = 0; m < 4; ++m) {
;                 const f32x4 a0 = acc[ai][0][m][0], a1 = acc[ai][0][m][1], b0 = acc[ai][1][m][0], b1 = acc[ai][1][m][1];
;                 u32x4 w;
;                 w.x = cvt_pk_bf16(silu_f(a0[0]) * b0[0], silu_f(a0[1]) * b0[1]); w.y = cvt_pk_bf16(silu_f(a0[2]) * b0[2], silu_f(a0[3]) * b0[3]);
;                 w.z = cvt_pk_bf16(silu_f(a1[0]) * b1[0], silu_f(a1[1]) * b1[1]); w.w = cvt_pk_bf16(silu_f(a1[2]) * b1[2], silu_f(a1[3]) * b1[3]);
;                 *(u32x4*)(H + (size_t)(row0 + ai * 128 + m * 16) * DFF + hc0) = w;
;             }
	v_mul_f32_e32 v105, v110, v108
	v_mul_f32_e32 v108, 0xbfb8aa3b, v100
	v_mul_f32_e32 v105, v105, v106
	v_mul_f32_e32 v106, v111, v109
	v_exp_f32_e32 v108, v108
	v_mul_f32_e32 v109, 0xbfb8aa3b, v101
	v_exp_f32_e32 v109, v109
	v_mul_f32_e32 v106, v106, v107
	v_add_f32_e32 v107, 1.0, v108
	v_rcp_f32_e32 v107, v107
	v_add_f32_e32 v108, 1.0, v109
	v_rcp_f32_e32 v108, v108
	v_cvt_pk_bf16_f32 v105, v105, v106
	v_mul_f32_e32 v100, v100, v107
	v_mul_f32_e32 v96, v100, v96
	v_mul_f32_e32 v100, v101, v108
	v_mul_f32_e32 v101, 0xbfb8aa3b, v102
	v_exp_f32_e32 v101, v101
	v_mul_f32_e32 v106, 0xbfb8aa3b, v103
	v_exp_f32_e32 v106, v106
	v_mul_f32_e32 v97, v100, v97
	v_add_f32_e32 v100, 1.0, v101
	v_rcp_f32_e32 v100, v100
	v_add_f32_e32 v101, 1.0, v106
	v_rcp_f32_e32 v101, v101
	v_cvt_pk_bf16_f32 v106, v96, v97
	v_mul_f32_e32 v96, v102, v100
	v_mul_f32_e32 v96, v96, v98
	v_mul_f32_e32 v97, v103, v101
	v_mul_f32_e32 v98, 0xbfb8aa3b, v92
	v_mul_f32_e32 v97, v97, v99
	v_exp_f32_e32 v98, v98
	v_mul_f32_e32 v99, 0xbfb8aa3b, v93
	v_exp_f32_e32 v99, v99
	v_cvt_pk_bf16_f32 v107, v96, v97
	v_add_f32_e32 v98, 1.0, v98
	v_rcp_f32_e32 v98, v98
	v_add_f32_e32 v99, 1.0, v99
	v_rcp_f32_e32 v99, v99
	v_add_u32_e32 v96, 16, v150
	v_mad_i64_i32 v[96:97], s[14:15], v96, s42, v[112:113]
	v_mul_f32_e32 v92, v92, v98
	v_lshl_add_u64 v[96:97], v[96:97], 0, v[114:115]
	v_mul_f32_e32 v88, v92, v88
	v_mul_f32_e32 v92, v93, v99
	v_mul_f32_e32 v93, 0xbfb8aa3b, v94
	global_store_dwordx4 v[96:97], v[104:107], off
	v_exp_f32_e32 v93, v93
	v_mul_f32_e32 v96, 0xbfb8aa3b, v95
	v_exp_f32_e32 v96, v96
	v_mul_f32_e32 v89, v92, v89
	v_add_f32_e32 v92, 1.0, v93
	v_rcp_f32_e32 v92, v92
	v_add_f32_e32 v93, 1.0, v96
	v_rcp_f32_e32 v93, v93
	v_cvt_pk_bf16_f32 v88, v88, v89
	v_mul_f32_e32 v89, v94, v92
	v_mul_f32_e32 v92, 0xbfb8aa3b, v84
	v_mul_f32_e32 v89, v89, v90
	v_mul_f32_e32 v90, v95, v93
	v_exp_f32_e32 v92, v92
	v_mul_f32_e32 v93, 0xbfb8aa3b, v85
	v_exp_f32_e32 v93, v93
	v_mul_f32_e32 v90, v90, v91
	v_add_f32_e32 v91, 1.0, v92
	v_rcp_f32_e32 v91, v91
	v_add_f32_e32 v92, 1.0, v93
	v_rcp_f32_e32 v92, v92
	v_cvt_pk_bf16_f32 v89, v89, v90
	v_mul_f32_e32 v84, v84, v91
	v_mul_f32_e32 v80, v84, v80
	v_mul_f32_e32 v84, v85, v92
	v_mul_f32_e32 v85, 0xbfb8aa3b, v86
	v_exp_f32_e32 v85, v85
	v_mul_f32_e32 v90, 0xbfb8aa3b, v87
	v_exp_f32_e32 v90, v90
	v_mul_f32_e32 v81, v84, v81
	v_add_f32_e32 v84, 1.0, v85
	v_rcp_f32_e32 v84, v84
	v_add_f32_e32 v85, 1.0, v90
	v_rcp_f32_e32 v85, v85
	v_cvt_pk_bf16_f32 v90, v80, v81
	v_mul_f32_e32 v80, v86, v84
	v_mul_f32_e32 v80, v80, v82
	v_mul_f32_e32 v81, v87, v85
	v_mul_f32_e32 v82, 0xbfb8aa3b, v76
	v_mul_f32_e32 v81, v81, v83
	v_exp_f32_e32 v82, v82
	v_mul_f32_e32 v83, 0xbfb8aa3b, v77
	v_exp_f32_e32 v83, v83
	v_cvt_pk_bf16_f32 v91, v80, v81
	v_add_f32_e32 v82, 1.0, v82
	v_rcp_f32_e32 v82, v82
	v_add_f32_e32 v83, 1.0, v83
	v_rcp_f32_e32 v83, v83
	v_add_u32_e32 v80, 32, v150
	v_mad_i64_i32 v[80:81], s[14:15], v80, s42, v[112:113]
	v_mul_f32_e32 v76, v76, v82
	v_lshl_add_u64 v[80:81], v[80:81], 0, v[114:115]
	v_mul_f32_e32 v72, v76, v72
	v_mul_f32_e32 v76, v77, v83
	v_mul_f32_e32 v77, 0xbfb8aa3b, v78
	global_store_dwordx4 v[80:81], v[88:91], off
	v_exp_f32_e32 v77, v77
	v_mul_f32_e32 v80, 0xbfb8aa3b, v79
	v_exp_f32_e32 v80, v80
	v_mul_f32_e32 v73, v76, v73
	v_add_f32_e32 v76, 1.0, v77
	v_rcp_f32_e32 v76, v76
	v_add_f32_e32 v77, 1.0, v80
	v_rcp_f32_e32 v77, v77
	v_cvt_pk_bf16_f32 v72, v72, v73
	v_mul_f32_e32 v73, v78, v76
	v_mul_f32_e32 v76, 0xbfb8aa3b, v68
	v_mul_f32_e32 v73, v73, v74
	v_mul_f32_e32 v74, v79, v77
	v_exp_f32_e32 v76, v76
	v_mul_f32_e32 v77, 0xbfb8aa3b, v69
	v_exp_f32_e32 v77, v77
	v_mul_f32_e32 v74, v74, v75
	v_add_f32_e32 v75, 1.0, v76
	v_rcp_f32_e32 v75, v75
	v_add_f32_e32 v76, 1.0, v77
	v_rcp_f32_e32 v76, v76
	v_cvt_pk_bf16_f32 v73, v73, v74
	v_mul_f32_e32 v68, v68, v75
	v_mul_f32_e32 v64, v68, v64
	v_mul_f32_e32 v68, v69, v76
	v_mul_f32_e32 v69, 0xbfb8aa3b, v70
	v_exp_f32_e32 v69, v69
	v_mul_f32_e32 v74, 0xbfb8aa3b, v71
	v_exp_f32_e32 v74, v74
	v_mul_f32_e32 v65, v68, v65
	v_add_f32_e32 v68, 1.0, v69
	v_rcp_f32_e32 v68, v68
	v_add_f32_e32 v69, 1.0, v74
	v_rcp_f32_e32 v69, v69
	v_cvt_pk_bf16_f32 v74, v64, v65
	v_mul_f32_e32 v64, v70, v68
	v_mul_f32_e32 v64, v64, v66
	v_mul_f32_e32 v65, v71, v69
	v_mul_f32_e32 v66, 0xbfb8aa3b, v60
	v_mul_f32_e32 v65, v65, v67
	v_exp_f32_e32 v66, v66
	v_mul_f32_e32 v67, 0xbfb8aa3b, v61
	v_cvt_pk_bf16_f32 v75, v64, v65
	v_add_u32_e32 v64, 48, v150
	v_exp_f32_e32 v67, v67
	v_mad_i64_i32 v[64:65], s[14:15], v64, s42, v[112:113]
	v_lshl_add_u64 v[64:65], v[64:65], 0, v[114:115]
	global_store_dwordx4 v[64:65], v[72:75], off
	v_add_f32_e32 v64, 1.0, v66
	v_rcp_f32_e32 v64, v64
	v_add_f32_e32 v65, 1.0, v67
	v_rcp_f32_e32 v65, v65
	v_add_u32_e32 v66, 0x80, v150
	v_mul_f32_e32 v60, v60, v64
	v_mul_f32_e32 v52, v60, v52
	v_mul_f32_e32 v60, v61, v65
	v_mul_f32_e32 v61, 0xbfb8aa3b, v62
	v_exp_f32_e32 v61, v61
	v_mul_f32_e32 v64, 0xbfb8aa3b, v63
	v_exp_f32_e32 v64, v64
	v_mul_f32_e32 v53, v60, v53
	v_add_f32_e32 v60, 1.0, v61
	v_rcp_f32_e32 v60, v60
	v_add_f32_e32 v61, 1.0, v64
	v_rcp_f32_e32 v61, v61
	v_cvt_pk_bf16_f32 v52, v52, v53
	v_mul_f32_e32 v53, v62, v60
	v_mul_f32_e32 v60, 0xbfb8aa3b, v56
	v_exp_f32_e32 v60, v60
	v_mul_f32_e32 v53, v53, v54
	v_mul_f32_e32 v54, v63, v61
	v_mul_f32_e32 v61, 0xbfb8aa3b, v57
	v_exp_f32_e32 v61, v61
	v_mul_f32_e32 v54, v54, v55
	v_add_f32_e32 v55, 1.0, v60
	v_rcp_f32_e32 v55, v55
	v_add_f32_e32 v60, 1.0, v61
	v_rcp_f32_e32 v60, v60
	v_cvt_pk_bf16_f32 v53, v53, v54
	v_mul_f32_e32 v54, v56, v55
	v_mul_f32_e32 v55, 0xbfb8aa3b, v58
	v_exp_f32_e32 v55, v55
	v_mul_f32_e32 v56, 0xbfb8aa3b, v59
; __device__ __forceinline__ unsigned cvt_pk_bf16(float lo, float hi) { unsigned r; asm volatile("v_cvt_pk_bf16_f32 %0, %1, %2" : "=v"(r) : "v"(lo), "v"(hi)); return r; }
; __device__ __forceinline__ float silu_f(float a) { return a * __builtin_amdgcn_rcpf(1.0f + __expf(-a)); }
; template <class Epi, class Sched>
; __device__ __forceinline__ void gemm_phase(LAS unsigned char* lds, const Gemm g, const Sched& S, const Epi& E) {
;     ...
;         E(acc, cur, wr, wc, fr, fq);
;         if (!has_next) break;
;     __device__ __forceinline__ void operator()(const AccT& acc, const Unit& u, int wr, int wc, int fr, int fq) const {
;     ...
;         const int row0 = u.pm * 256 + wr * 64 + fr, hc0 = u.pn * 128 + wc * 32 + 8 * fq;
; #pragma unroll
;         for (int ai = 0; ai < 2; ++ai)
; #pragma unroll
;             for (int m = 0; m < 4; ++m) {
;                 const f32x4 a0 = acc[ai][0][m][0], a1 = acc[ai][0][m][1], b0 = acc[ai][1][m][0], b1 = acc[ai][1][m][1];
;                 u32x4 w;
;                 w.x = cvt_pk_bf16(silu_f(a0[0]) * b0[0], silu_f(a0[1]) * b0[1]); w.y = cvt_pk_bf16(silu_f(a0[2]) * b0[2], silu_f(a0[3]) * b0[3]);
;                 w.z = cvt_pk_bf16(silu_f(a1[0]) * b1[0], silu_f(a1[1]) * b1[1]); w.w = cvt_pk_bf16(silu_f(a1[2]) * b1[2], silu_f(a1[3]) * b1[3]);
;                 *(u32x4*)(H + (size_t)(row0 + ai * 128 + m * 16) * DFF + hc0) = w;
;             }
	v_exp_f32_e32 v56, v56
	v_mul_f32_e32 v48, v54, v48
	v_mul_f32_e32 v54, v57, v60
	v_mul_f32_e32 v49, v54, v49
	v_add_f32_e32 v54, 1.0, v55
	v_rcp_f32_e32 v55, v54
	v_add_f32_e32 v54, 1.0, v56
	v_rcp_f32_e32 v56, v54
	v_cvt_pk_bf16_f32 v54, v48, v49
	v_mul_f32_e32 v48, v58, v55
	v_mul_f32_e32 v48, v48, v50
	v_mul_f32_e32 v49, v59, v56
	v_mul_f32_e32 v50, 0xbfb8aa3b, v44
	v_mul_f32_e32 v49, v49, v51
	v_exp_f32_e32 v50, v50
	v_mul_f32_e32 v51, 0xbfb8aa3b, v45
	v_exp_f32_e32 v51, v51
	v_cvt_pk_bf16_f32 v55, v48, v49
	v_add_f32_e32 v50, 1.0, v50
	v_rcp_f32_e32 v50, v50
	v_add_f32_e32 v51, 1.0, v51
	v_rcp_f32_e32 v51, v51
	v_mad_i64_i32 v[48:49], s[14:15], v66, s42, v[112:113]
	v_mul_f32_e32 v44, v44, v50
	v_mul_f32_e32 v36, v44, v36
	v_mul_f32_e32 v44, v45, v51
	v_mul_f32_e32 v45, 0xbfb8aa3b, v46
	v_exp_f32_e32 v45, v45
	v_lshl_add_u64 v[48:49], v[48:49], 0, v[114:115]
	global_store_dwordx4 v[48:49], v[52:55], off
	v_mul_f32_e32 v48, 0xbfb8aa3b, v47
	v_exp_f32_e32 v48, v48
	v_mul_f32_e32 v37, v44, v37
	v_add_f32_e32 v44, 1.0, v45
	v_rcp_f32_e32 v44, v44
	v_add_f32_e32 v45, 1.0, v48
	v_rcp_f32_e32 v45, v45
	v_cvt_pk_bf16_f32 v36, v36, v37
	v_mul_f32_e32 v37, v46, v44
	v_mul_f32_e32 v44, 0xbfb8aa3b, v40
	v_exp_f32_e32 v44, v44
	v_mul_f32_e32 v37, v37, v38
	v_mul_f32_e32 v38, v47, v45
	v_mul_f32_e32 v45, 0xbfb8aa3b, v41
	v_exp_f32_e32 v45, v45
	v_mul_f32_e32 v38, v38, v39
	v_add_f32_e32 v39, 1.0, v44
	v_rcp_f32_e32 v39, v39
	v_add_f32_e32 v44, 1.0, v45
	v_rcp_f32_e32 v44, v44
	v_cvt_pk_bf16_f32 v37, v37, v38
	v_mul_f32_e32 v38, v40, v39
	v_mul_f32_e32 v39, 0xbfb8aa3b, v42
	v_exp_f32_e32 v39, v39
	v_mul_f32_e32 v40, 0xbfb8aa3b, v43
	v_exp_f32_e32 v40, v40
	v_mul_f32_e32 v32, v38, v32
	v_mul_f32_e32 v38, v41, v44
	v_mul_f32_e32 v33, v38, v33
	v_add_f32_e32 v38, 1.0, v39
	v_rcp_f32_e32 v39, v38
	v_add_f32_e32 v38, 1.0, v40
	v_rcp_f32_e32 v40, v38
	v_cvt_pk_bf16_f32 v38, v32, v33
	v_mul_f32_e32 v32, v42, v39
	v_mul_f32_e32 v32, v32, v34
	v_mul_f32_e32 v33, v43, v40
	v_mul_f32_e32 v34, 0xbfb8aa3b, v28
	v_mul_f32_e32 v33, v33, v35
	v_exp_f32_e32 v34, v34
	v_mul_f32_e32 v35, 0xbfb8aa3b, v29
	v_exp_f32_e32 v35, v35
	v_cvt_pk_bf16_f32 v39, v32, v33
	v_add_f32_e32 v34, 1.0, v34
	v_rcp_f32_e32 v34, v34
	v_add_f32_e32 v35, 1.0, v35
	v_rcp_f32_e32 v35, v35
	v_add_u32_e32 v32, 0x90, v150
	v_mul_f32_e32 v28, v28, v34
	v_mul_f32_e32 v20, v28, v20
	v_mul_f32_e32 v28, v29, v35
	v_mul_f32_e32 v29, 0xbfb8aa3b, v30
	v_exp_f32_e32 v29, v29
	v_mad_i64_i32 v[32:33], s[14:15], v32, s42, v[112:113]
	v_lshl_add_u64 v[32:33], v[32:33], 0, v[114:115]
	global_store_dwordx4 v[32:33], v[36:39], off
	v_mul_f32_e32 v32, 0xbfb8aa3b, v31
	v_exp_f32_e32 v32, v32
	v_mul_f32_e32 v21, v28, v21
	v_add_f32_e32 v28, 1.0, v29
	v_rcp_f32_e32 v28, v28
	v_add_f32_e32 v29, 1.0, v32
	v_rcp_f32_e32 v29, v29
	v_cvt_pk_bf16_f32 v20, v20, v21
	v_mul_f32_e32 v21, v30, v28
	v_mul_f32_e32 v28, 0xbfb8aa3b, v24
	v_exp_f32_e32 v28, v28
	v_mul_f32_e32 v21, v21, v22
	v_mul_f32_e32 v22, v31, v29
	v_mul_f32_e32 v29, 0xbfb8aa3b, v25
	v_exp_f32_e32 v29, v29
	v_mul_f32_e32 v22, v22, v23
	v_add_f32_e32 v23, 1.0, v28
	v_rcp_f32_e32 v23, v23
	v_add_f32_e32 v28, 1.0, v29
	v_rcp_f32_e32 v28, v28
	v_cvt_pk_bf16_f32 v21, v21, v22
	v_mul_f32_e32 v22, v24, v23
	v_mul_f32_e32 v23, 0xbfb8aa3b, v26
	v_exp_f32_e32 v23, v23
	v_mul_f32_e32 v24, 0xbfb8aa3b, v27
	v_exp_f32_e32 v24, v24
	v_mul_f32_e32 v16, v22, v16
	v_mul_f32_e32 v22, v25, v28
	v_mul_f32_e32 v17, v22, v17
	v_add_f32_e32 v22, 1.0, v23
	v_rcp_f32_e32 v23, v22
	v_add_f32_e32 v22, 1.0, v24
	v_rcp_f32_e32 v24, v22
	v_cvt_pk_bf16_f32 v22, v16, v17
	v_mul_f32_e32 v16, v26, v23
	v_mul_f32_e32 v16, v16, v18
	v_mul_f32_e32 v17, v27, v24
	v_mul_f32_e32 v18, 0xbfb8aa3b, v12
	v_mul_f32_e32 v17, v17, v19
	v_exp_f32_e32 v18, v18
	v_mul_f32_e32 v19, 0xbfb8aa3b, v13
	v_exp_f32_e32 v19, v19
	v_cvt_pk_bf16_f32 v23, v16, v17
	v_add_f32_e32 v18, 1.0, v18
	v_rcp_f32_e32 v18, v18
	v_add_f32_e32 v19, 1.0, v19
	v_rcp_f32_e32 v19, v19
	v_add_u32_e32 v16, 0xa0, v150
	v_mul_f32_e32 v12, v12, v18
	v_mul_f32_e32 v4, v12, v4
	v_mul_f32_e32 v12, v13, v19
	v_mul_f32_e32 v13, 0xbfb8aa3b, v14
	v_exp_f32_e32 v13, v13
	v_mad_i64_i32 v[16:17], s[14:15], v16, s42, v[112:113]
	v_lshl_add_u64 v[16:17], v[16:17], 0, v[114:115]
	global_store_dwordx4 v[16:17], v[20:23], off
	v_mul_f32_e32 v16, 0xbfb8aa3b, v15
	v_exp_f32_e32 v16, v16
	v_mul_f32_e32 v5, v12, v5
	v_add_f32_e32 v12, 1.0, v13
	v_rcp_f32_e32 v12, v12
	v_add_f32_e32 v13, 1.0, v16
	v_rcp_f32_e32 v13, v13
	v_cvt_pk_bf16_f32 v4, v4, v5
	v_mul_f32_e32 v5, v14, v12
	v_mul_f32_e32 v12, 0xbfb8aa3b, v8
	v_exp_f32_e32 v12, v12
	v_mul_f32_e32 v5, v5, v6
	v_mul_f32_e32 v6, v15, v13
	v_mul_f32_e32 v13, 0xbfb8aa3b, v9
	v_exp_f32_e32 v13, v13
	v_mul_f32_e32 v6, v6, v7
	v_add_f32_e32 v7, 1.0, v12
	v_rcp_f32_e32 v7, v7
	v_add_f32_e32 v12, 1.0, v13
	v_rcp_f32_e32 v12, v12
	v_cvt_pk_bf16_f32 v5, v5, v6
	v_mul_f32_e32 v6, v8, v7
	v_mul_f32_e32 v7, 0xbfb8aa3b, v10
	v_exp_f32_e32 v7, v7
	v_mul_f32_e32 v8, 0xbfb8aa3b, v11
	v_exp_f32_e32 v8, v8
	v_mul_f32_e32 v0, v6, v0
	v_mul_f32_e32 v6, v9, v12
	v_mul_f32_e32 v1, v6, v1
	v_add_f32_e32 v6, 1.0, v7
	v_rcp_f32_e32 v7, v6
	v_add_f32_e32 v6, 1.0, v8
	v_rcp_f32_e32 v8, v6
	v_cvt_pk_bf16_f32 v6, v0, v1
	v_mul_f32_e32 v0, v10, v7
	v_mul_f32_e32 v0, v0, v2
	v_mul_f32_e32 v1, v11, v8
	v_mul_f32_e32 v1, v1, v3
	v_cvt_pk_bf16_f32 v7, v0, v1
	v_add_u32_e32 v0, 0xb0, v150
	v_mad_i64_i32 v[0:1], s[14:15], v0, s42, v[112:113]
	v_lshl_add_u64 v[0:1], v[0:1], 0, v[114:115]
	s_and_b64 vcc, exec, s[2:3]
	s_mov_b32 s43, s4
	s_mov_b32 s12, s6
	s_mov_b64 s[18:19], s[10:11]
	s_mov_b64 s[14:15], s[8:9]
	global_store_dwordx4 v[0:1], v[4:7], off
	s_cbranch_vccz .LBB0_232
	s_branch .Lconc_end_g0
; __device__ __forceinline__ unsigned cvt_pk_bf16(float lo, float hi) { unsigned r; asm volatile("v_cvt_pk_bf16_f32 %0, %1, %2" : "=v"(r) : "v"(lo), "v"(hi)); return r; }
; __device__ __forceinline__ float silu_f(float a) { return a * __builtin_amdgcn_rcpf(1.0f + __expf(-a)); }
;     __device__ __forceinline__ void operator()(const AccT& acc, const Unit& u, int wr, int wc, int fr, int fq) const {
;     ...
;         const int row0 = u.pm * 256 + wr * 64 + fr, hc0 = u.pn * 128 + wc * 32 + 8 * fq;
; #pragma unroll
;         for (int ai = 0; ai < 2; ++ai)
; #pragma unroll
;             for (int m = 0; m < 4; ++m) {
;                 const f32x4 a0 = acc[ai][0][m][0], a1 = acc[ai][0][m][1], b0 = acc[ai][1][m][0], b1 = acc[ai][1][m][1];
;                 u32x4 w;
;                 w.x = cvt_pk_bf16(silu_f(a0[0]) * b0[0], silu_f(a0[1]) * b0[1]); w.y = cvt_pk_bf16(silu_f(a0[2]) * b0[2], silu_f(a0[3]) * b0[3]);
;                 w.z = cvt_pk_bf16(silu_f(a1[0]) * b1[0], silu_f(a1[1]) * b1[1]); w.w = cvt_pk_bf16(silu_f(a1[2]) * b1[2], silu_f(a1[3]) * b1[3]);
;                 *(u32x4*)(H + (size_t)(row0 + ai * 128 + m * 16) * DFF + hc0) = w;
;             }
.Lconc_epi1_g0:
	v_mul_f32_e32 v152, 0xbfb8aa3b, v124
	v_mov_b32_e32 v151, v145
	v_mov_b32_e32 v150, v144
	s_lshl_b32 s5, s12, 8
	v_exp_f32_e32 v153, v152
	v_mul_f32_e32 v152, 0xbfb8aa3b, v125
	s_add_i32 s5, s5, s34
	v_exp_f32_e32 v154, v152
	v_add_u32_e32 v150, s5, v150
	s_lshl_b32 s5, s43, 7
	s_or_b32 s5, s5, s35
	v_lshl_add_u32 v152, v151, 3, s5
	v_add_f32_e32 v151, 1.0, v153
	v_rcp_f32_e32 v151, v151
	v_add_f32_e32 v153, 1.0, v154
	v_rcp_f32_e32 v154, v153
	v_ashrrev_i32_e32 v153, 31, v152
	v_mul_f32_e32 v124, v124, v151
	v_mul_f32_e32 v120, v124, v120
	v_mul_f32_e32 v124, v125, v154
	v_mul_f32_e32 v125, 0xbfb8aa3b, v126
	v_exp_f32_e32 v125, v125
	v_mul_f32_e32 v151, 0xbfb8aa3b, v127
	v_exp_f32_e32 v151, v151
	v_mul_f32_e32 v121, v124, v121
	v_add_f32_e32 v124, 1.0, v125
	v_rcp_f32_e32 v124, v124
	v_add_f32_e32 v125, 1.0, v151
	v_rcp_f32_e32 v125, v125
	v_cvt_pk_bf16_f32 v120, v120, v121
	v_mul_f32_e32 v121, v126, v124
	v_mul_f32_e32 v124, 0xbfb8aa3b, v116
	v_mul_f32_e32 v121, v121, v122
	v_mul_f32_e32 v122, v127, v125
	v_exp_f32_e32 v124, v124
	v_mul_f32_e32 v125, 0xbfb8aa3b, v117
	v_exp_f32_e32 v125, v125
	v_mul_f32_e32 v122, v122, v123
	v_add_f32_e32 v123, 1.0, v124
	v_rcp_f32_e32 v123, v123
	v_add_f32_e32 v124, 1.0, v125
	v_rcp_f32_e32 v124, v124
	v_cvt_pk_bf16_f32 v121, v121, v122
	v_mul_f32_e32 v116, v116, v123
	v_mul_f32_e32 v112, v116, v112
	v_mul_f32_e32 v116, v117, v124
	v_mul_f32_e32 v117, 0xbfb8aa3b, v118
	v_exp_f32_e32 v117, v117
	v_mul_f32_e32 v122, 0xbfb8aa3b, v119
	v_exp_f32_e32 v122, v122
	v_mul_f32_e32 v113, v116, v113
	v_add_f32_e32 v116, 1.0, v117
	v_rcp_f32_e32 v116, v116
	v_add_f32_e32 v117, 1.0, v122
	v_rcp_f32_e32 v117, v117
	v_cvt_pk_bf16_f32 v122, v112, v113
	v_mul_f32_e32 v112, v118, v116
	v_mul_f32_e32 v118, 0xbfb8aa3b, v108
	v_mul_f32_e32 v113, v119, v117
	v_exp_f32_e32 v118, v118
	v_mul_f32_e32 v119, 0xbfb8aa3b, v109
	v_exp_f32_e32 v119, v119
	v_mul_f32_e32 v112, v112, v114
	v_add_f32_e32 v118, 1.0, v118
	v_rcp_f32_e32 v118, v118
	v_add_f32_e32 v119, 1.0, v119
	v_rcp_f32_e32 v119, v119
	v_mul_f32_e32 v113, v113, v115
	v_cvt_pk_bf16_f32 v123, v112, v113
	v_mov_b64_e32 v[112:113], s[82:83]
	v_mad_i64_i32 v[116:117], s[14:15], v150, s42, v[112:113]
	v_lshlrev_b64 v[114:115], 1, v[152:153]
	v_mul_f32_e32 v108, v108, v118
	v_lshl_add_u64 v[116:117], v[116:117], 0, v[114:115]
	v_mul_f32_e32 v104, v108, v104
	v_mul_f32_e32 v108, v109, v119
	v_mul_f32_e32 v109, 0xbfb8aa3b, v110
	global_store_dwordx4 v[116:117], v[120:123], off
	v_exp_f32_e32 v109, v109
	v_mul_f32_e32 v116, 0xbfb8aa3b, v111
	v_exp_f32_e32 v116, v116
	v_mul_f32_e32 v105, v108, v105
	v_add_f32_e32 v108, 1.0, v109
	v_rcp_f32_e32 v108, v108
	v_add_f32_e32 v109, 1.0, v116
	v_rcp_f32_e32 v109, v109
	v_cvt_pk_bf16_f32 v104, v104, v105
	v_mul_f32_e32 v105, v110, v108
	v_mul_f32_e32 v108, 0xbfb8aa3b, v100
	v_mul_f32_e32 v105, v105, v106
	v_mul_f32_e32 v106, v111, v109
	v_exp_f32_e32 v108, v108
	v_mul_f32_e32 v109, 0xbfb8aa3b, v101
	v_exp_f32_e32 v109, v109
	v_mul_f32_e32 v106, v106, v107
	v_add_f32_e32 v107, 1.0, v108
	v_rcp_f32_e32 v107, v107
	v_add_f32_e32 v108, 1.0, v109
	v_rcp_f32_e32 v108, v108
	v_cvt_pk_bf16_f32 v105, v105, v106
	v_mul_f32_e32 v100, v100, v107
	v_mul_f32_e32 v96, v100, v96
	v_mul_f32_e32 v100, v101, v108
	v_mul_f32_e32 v101, 0xbfb8aa3b, v102
	v_exp_f32_e32 v101, v101
	v_mul_f32_e32 v106, 0xbfb8aa3b, v103
	v_exp_f32_e32 v106, v106
	v_mul_f32_e32 v97, v100, v97
	v_add_f32_e32 v100, 1.0, v101
	v_rcp_f32_e32 v100, v100
	v_add_f32_e32 v101, 1.0, v106
	v_rcp_f32_e32 v101, v101
	v_cvt_pk_bf16_f32 v106, v96, v97
	v_mul_f32_e32 v96, v102, v100
	v_mul_f32_e32 v96, v96, v98
	v_mul_f32_e32 v97, v103, v101
	v_mul_f32_e32 v98, 0xbfb8aa3b, v92
	v_mul_f32_e32 v97, v97, v99
	v_exp_f32_e32 v98, v98
	v_mul_f32_e32 v99, 0xbfb8aa3b, v93
	v_exp_f32_e32 v99, v99
	v_cvt_pk_bf16_f32 v107, v96, v97
	v_add_f32_e32 v98, 1.0, v98
	v_rcp_f32_e32 v98, v98
	v_add_f32_e32 v99, 1.0, v99
	v_rcp_f32_e32 v99, v99
	v_add_u32_e32 v96, 16, v150
	v_mad_i64_i32 v[96:97], s[14:15], v96, s42, v[112:113]
	v_mul_f32_e32 v92, v92, v98
	v_lshl_add_u64 v[96:97], v[96:97], 0, v[114:115]
	v_mul_f32_e32 v88, v92, v88
	v_mul_f32_e32 v92, v93, v99
	v_mul_f32_e32 v93, 0xbfb8aa3b, v94
	global_store_dwordx4 v[96:97], v[104:107], off
	v_exp_f32_e32 v93, v93
	v_mul_f32_e32 v96, 0xbfb8aa3b, v95
	v_exp_f32_e32 v96, v96
	v_mul_f32_e32 v89, v92, v89
	v_add_f32_e32 v92, 1.0, v93
	v_rcp_f32_e32 v92, v92
	v_add_f32_e32 v93, 1.0, v96
	v_rcp_f32_e32 v93, v93
	v_cvt_pk_bf16_f32 v88, v88, v89
	v_mul_f32_e32 v89, v94, v92
	v_mul_f32_e32 v92, 0xbfb8aa3b, v84
	v_mul_f32_e32 v89, v89, v90
	v_mul_f32_e32 v90, v95, v93
	v_exp_f32_e32 v92, v92
	v_mul_f32_e32 v93, 0xbfb8aa3b, v85
	v_exp_f32_e32 v93, v93
	v_mul_f32_e32 v90, v90, v91
	v_add_f32_e32 v91, 1.0, v92
	v_rcp_f32_e32 v91, v91
	v_add_f32_e32 v92, 1.0, v93
	v_rcp_f32_e32 v92, v92
	v_cvt_pk_bf16_f32 v89, v89, v90
	v_mul_f32_e32 v84, v84, v91
	v_mul_f32_e32 v80, v84, v80
	v_mul_f32_e32 v84, v85, v92
	v_mul_f32_e32 v85, 0xbfb8aa3b, v86
	v_exp_f32_e32 v85, v85
	v_mul_f32_e32 v90, 0xbfb8aa3b, v87
	v_exp_f32_e32 v90, v90
	v_mul_f32_e32 v81, v84, v81
	v_add_f32_e32 v84, 1.0, v85
	v_rcp_f32_e32 v84, v84
	v_add_f32_e32 v85, 1.0, v90
	v_rcp_f32_e32 v85, v85
	v_cvt_pk_bf16_f32 v90, v80, v81
	v_mul_f32_e32 v80, v86, v84
	v_mul_f32_e32 v80, v80, v82
	v_mul_f32_e32 v81, v87, v85
	v_mul_f32_e32 v82, 0xbfb8aa3b, v76
	v_mul_f32_e32 v81, v81, v83
	v_exp_f32_e32 v82, v82
	v_mul_f32_e32 v83, 0xbfb8aa3b, v77
	v_exp_f32_e32 v83, v83
	v_cvt_pk_bf16_f32 v91, v80, v81
	v_add_f32_e32 v82, 1.0, v82
	v_rcp_f32_e32 v82, v82
	v_add_f32_e32 v83, 1.0, v83
	v_rcp_f32_e32 v83, v83
; __device__ __forceinline__ unsigned cvt_pk_bf16(float lo, float hi) { unsigned r; asm volatile("v_cvt_pk_bf16_f32 %0, %1, %2" : "=v"(r) : "v"(lo), "v"(hi)); return r; }
; __device__ __forceinline__ float silu_f(float a) { return a * __builtin_amdgcn_rcpf(1.0f + __expf(-a)); }
;     __device__ __forceinline__ void operator()(const AccT& acc, const Unit& u, int wr, int wc, int fr, int fq) const {
;     ...
;         const int row0 = u.pm * 256 + wr * 64 + fr, hc0 = u.pn * 128 + wc * 32 + 8 * fq;
; #pragma unroll
;         for (int ai = 0; ai < 2; ++ai)
; #pragma unroll
;             for (int m = 0; m < 4; ++m) {
;                 const f32x4 a0 = acc[ai][0][m][0], a1 = acc[ai][0][m][1], b0 = acc[ai][1][m][0], b1 = acc[ai][1][m][1];
;                 u32x4 w;
;                 w.x = cvt_pk_bf16(silu_f(a0[0]) * b0[0], silu_f(a0[1]) * b0[1]); w.y = cvt_pk_bf16(silu_f(a0[2]) * b0[2], silu_f(a0[3]) * b0[3]);
;                 w.z = cvt_pk_bf16(silu_f(a1[0]) * b1[0], silu_f(a1[1]) * b1[1]); w.w = cvt_pk_bf16(silu_f(a1[2]) * b1[2], silu_f(a1[3]) * b1[3]);
;                 *(u32x4*)(H + (size_t)(row0 + ai * 128 + m * 16) * DFF + hc0) = w;
;             }
	v_add_u32_e32 v80, 32, v150
	v_mad_i64_i32 v[80:81], s[14:15], v80, s42, v[112:113]
	v_mul_f32_e32 v76, v76, v82
	v_lshl_add_u64 v[80:81], v[80:81], 0, v[114:115]
	v_mul_f32_e32 v72, v76, v72
	v_mul_f32_e32 v76, v77, v83
	v_mul_f32_e32 v77, 0xbfb8aa3b, v78
	global_store_dwordx4 v[80:81], v[88:91], off
	v_exp_f32_e32 v77, v77
	v_mul_f32_e32 v80, 0xbfb8aa3b, v79
	v_exp_f32_e32 v80, v80
	v_mul_f32_e32 v73, v76, v73
	v_add_f32_e32 v76, 1.0, v77
	v_rcp_f32_e32 v76, v76
	v_add_f32_e32 v77, 1.0, v80
	v_rcp_f32_e32 v77, v77
	v_cvt_pk_bf16_f32 v72, v72, v73
	v_mul_f32_e32 v73, v78, v76
	v_mul_f32_e32 v76, 0xbfb8aa3b, v68
	v_mul_f32_e32 v73, v73, v74
	v_mul_f32_e32 v74, v79, v77
	v_exp_f32_e32 v76, v76
	v_mul_f32_e32 v77, 0xbfb8aa3b, v69
	v_exp_f32_e32 v77, v77
	v_mul_f32_e32 v74, v74, v75
	v_add_f32_e32 v75, 1.0, v76
	v_rcp_f32_e32 v75, v75
	v_add_f32_e32 v76, 1.0, v77
	v_rcp_f32_e32 v76, v76
	v_cvt_pk_bf16_f32 v73, v73, v74
	v_mul_f32_e32 v68, v68, v75
	v_mul_f32_e32 v64, v68, v64
	v_mul_f32_e32 v68, v69, v76
	v_mul_f32_e32 v69, 0xbfb8aa3b, v70
	v_exp_f32_e32 v69, v69
	v_mul_f32_e32 v74, 0xbfb8aa3b, v71
	v_exp_f32_e32 v74, v74
	v_mul_f32_e32 v65, v68, v65
	v_add_f32_e32 v68, 1.0, v69
	v_rcp_f32_e32 v68, v68
	v_add_f32_e32 v69, 1.0, v74
	v_rcp_f32_e32 v69, v69
	v_cvt_pk_bf16_f32 v74, v64, v65
	v_mul_f32_e32 v64, v70, v68
	v_mul_f32_e32 v64, v64, v66
	v_mul_f32_e32 v65, v71, v69
	v_mul_f32_e32 v66, 0xbfb8aa3b, v60
	v_mul_f32_e32 v65, v65, v67
	v_exp_f32_e32 v66, v66
	v_mul_f32_e32 v67, 0xbfb8aa3b, v61
	v_cvt_pk_bf16_f32 v75, v64, v65
	v_add_u32_e32 v64, 48, v150
	v_exp_f32_e32 v67, v67
	v_mad_i64_i32 v[64:65], s[14:15], v64, s42, v[112:113]
	v_lshl_add_u64 v[64:65], v[64:65], 0, v[114:115]
	global_store_dwordx4 v[64:65], v[72:75], off
	v_add_f32_e32 v64, 1.0, v66
	v_rcp_f32_e32 v64, v64
	v_add_f32_e32 v65, 1.0, v67
	v_rcp_f32_e32 v65, v65
	v_add_u32_e32 v66, 0x80, v150
	v_mul_f32_e32 v60, v60, v64
	v_mul_f32_e32 v52, v60, v52
	v_mul_f32_e32 v60, v61, v65
	v_mul_f32_e32 v61, 0xbfb8aa3b, v62
	v_exp_f32_e32 v61, v61
	v_mul_f32_e32 v64, 0xbfb8aa3b, v63
	v_exp_f32_e32 v64, v64
	v_mul_f32_e32 v53, v60, v53
	v_add_f32_e32 v60, 1.0, v61
	v_rcp_f32_e32 v60, v60
	v_add_f32_e32 v61, 1.0, v64
	v_rcp_f32_e32 v61, v61
	v_cvt_pk_bf16_f32 v52, v52, v53
	v_mul_f32_e32 v53, v62, v60
	v_mul_f32_e32 v60, 0xbfb8aa3b, v56
	v_exp_f32_e32 v60, v60
	v_mul_f32_e32 v53, v53, v54
	v_mul_f32_e32 v54, v63, v61
	v_mul_f32_e32 v61, 0xbfb8aa3b, v57
	v_exp_f32_e32 v61, v61
	v_mul_f32_e32 v54, v54, v55
	v_add_f32_e32 v55, 1.0, v60
	v_rcp_f32_e32 v55, v55
	v_add_f32_e32 v60, 1.0, v61
	v_rcp_f32_e32 v60, v60
	v_cvt_pk_bf16_f32 v53, v53, v54
	v_mul_f32_e32 v54, v56, v55
	v_mul_f32_e32 v55, 0xbfb8aa3b, v58
	v_exp_f32_e32 v55, v55
	v_mul_f32_e32 v56, 0xbfb8aa3b, v59
	v_exp_f32_e32 v56, v56
	v_mul_f32_e32 v48, v54, v48
	v_mul_f32_e32 v54, v57, v60
	v_mul_f32_e32 v49, v54, v49
	v_add_f32_e32 v54, 1.0, v55
	v_rcp_f32_e32 v55, v54
	v_add_f32_e32 v54, 1.0, v56
	v_rcp_f32_e32 v56, v54
	v_cvt_pk_bf16_f32 v54, v48, v49
	v_mul_f32_e32 v48, v58, v55
	v_mul_f32_e32 v48, v48, v50
	v_mul_f32_e32 v49, v59, v56
	v_mul_f32_e32 v50, 0xbfb8aa3b, v44
	v_mul_f32_e32 v49, v49, v51
	v_exp_f32_e32 v50, v50
	v_mul_f32_e32 v51, 0xbfb8aa3b, v45
	v_exp_f32_e32 v51, v51
	v_cvt_pk_bf16_f32 v55, v48, v49
	v_add_f32_e32 v50, 1.0, v50
	v_rcp_f32_e32 v50, v50
	v_add_f32_e32 v51, 1.0, v51
	v_rcp_f32_e32 v51, v51
	v_mad_i64_i32 v[48:49], s[14:15], v66, s42, v[112:113]
	v_mul_f32_e32 v44, v44, v50
	v_mul_f32_e32 v36, v44, v36
	v_mul_f32_e32 v44, v45, v51
	v_mul_f32_e32 v45, 0xbfb8aa3b, v46
	v_exp_f32_e32 v45, v45
	v_lshl_add_u64 v[48:49], v[48:49], 0, v[114:115]
	global_store_dwordx4 v[48:49], v[52:55], off
	v_mul_f32_e32 v48, 0xbfb8aa3b, v47
	v_exp_f32_e32 v48, v48
	v_mul_f32_e32 v37, v44, v37
	v_add_f32_e32 v44, 1.0, v45
	v_rcp_f32_e32 v44, v44
	v_add_f32_e32 v45, 1.0, v48
	v_rcp_f32_e32 v45, v45
	v_cvt_pk_bf16_f32 v36, v36, v37
	v_mul_f32_e32 v37, v46, v44
	v_mul_f32_e32 v44, 0xbfb8aa3b, v40
	v_exp_f32_e32 v44, v44
	v_mul_f32_e32 v37, v37, v38
	v_mul_f32_e32 v38, v47, v45
	v_mul_f32_e32 v45, 0xbfb8aa3b, v41
	v_exp_f32_e32 v45, v45
	v_mul_f32_e32 v38, v38, v39
	v_add_f32_e32 v39, 1.0, v44
	v_rcp_f32_e32 v39, v39
	v_add_f32_e32 v44, 1.0, v45
	v_rcp_f32_e32 v44, v44
; __device__ __forceinline__ unsigned cvt_pk_bf16(float lo, float hi) { unsigned r; asm volatile("v_cvt_pk_bf16_f32 %0, %1, %2" : "=v"(r) : "v"(lo), "v"(hi)); return r; }
; __device__ __forceinline__ float silu_f(float a) { return a * __builtin_amdgcn_rcpf(1.0f + __expf(-a)); }
; #define PG8_WAIT_V(n) asm volatile("s_waitcnt vmcnt(" #n ")" ::: "memory")
; #define PG8_BAR __builtin_amdgcn_s_barrier()
; template <class Epi, class Sched>
; __device__ __forceinline__ void gemm_phase(LAS unsigned char* lds, const Gemm g, const Sched& S, const Epi& E) {
;     ...
;     PG8_WAIT_V(0);
;     if (wr == 0) PG8_BAR;
;     PG8_BAR;
;     __device__ __forceinline__ void operator()(const AccT& acc, const Unit& u, int wr, int wc, int fr, int fq) const {
;     ...
;         const int row0 = u.pm * 256 + wr * 64 + fr, hc0 = u.pn * 128 + wc * 32 + 8 * fq;
; #pragma unroll
;         for (int ai = 0; ai < 2; ++ai)
; #pragma unroll
;             for (int m = 0; m < 4; ++m) {
;                 const f32x4 a0 = acc[ai][0][m][0], a1 = acc[ai][0][m][1], b0 = acc[ai][1][m][0], b1 = acc[ai][1][m][1];
;                 u32x4 w;
;                 w.x = cvt_pk_bf16(silu_f(a0[0]) * b0[0], silu_f(a0[1]) * b0[1]); w.y = cvt_pk_bf16(silu_f(a0[2]) * b0[2], silu_f(a0[3]) * b0[3]);
;                 w.z = cvt_pk_bf16(silu_f(a1[0]) * b1[0], silu_f(a1[1]) * b1[1]); w.w = cvt_pk_bf16(silu_f(a1[2]) * b1[2], silu_f(a1[3]) * b1[3]);
;                 *(u32x4*)(H + (size_t)(row0 + ai * 128 + m * 16) * DFF + hc0) = w;
;             }
	v_cvt_pk_bf16_f32 v37, v37, v38
	v_mul_f32_e32 v38, v40, v39
	v_mul_f32_e32 v39, 0xbfb8aa3b, v42
	v_exp_f32_e32 v39, v39
	v_mul_f32_e32 v40, 0xbfb8aa3b, v43
	v_exp_f32_e32 v40, v40
	v_mul_f32_e32 v32, v38, v32
	v_mul_f32_e32 v38, v41, v44
	v_mul_f32_e32 v33, v38, v33
	v_add_f32_e32 v38, 1.0, v39
	v_rcp_f32_e32 v39, v38
	v_add_f32_e32 v38, 1.0, v40
	v_rcp_f32_e32 v40, v38
	v_cvt_pk_bf16_f32 v38, v32, v33
	v_mul_f32_e32 v32, v42, v39
	v_mul_f32_e32 v32, v32, v34
	v_mul_f32_e32 v33, v43, v40
	v_mul_f32_e32 v34, 0xbfb8aa3b, v28
	v_mul_f32_e32 v33, v33, v35
	v_exp_f32_e32 v34, v34
	v_mul_f32_e32 v35, 0xbfb8aa3b, v29
	v_exp_f32_e32 v35, v35
	v_cvt_pk_bf16_f32 v39, v32, v33
	v_add_f32_e32 v34, 1.0, v34
	v_rcp_f32_e32 v34, v34
	v_add_f32_e32 v35, 1.0, v35
	v_rcp_f32_e32 v35, v35
	v_add_u32_e32 v32, 0x90, v150
	v_mul_f32_e32 v28, v28, v34
	v_mul_f32_e32 v20, v28, v20
	v_mul_f32_e32 v28, v29, v35
	v_mul_f32_e32 v29, 0xbfb8aa3b, v30
	v_exp_f32_e32 v29, v29
	v_mad_i64_i32 v[32:33], s[14:15], v32, s42, v[112:113]
	v_lshl_add_u64 v[32:33], v[32:33], 0, v[114:115]
	global_store_dwordx4 v[32:33], v[36:39], off
	v_mul_f32_e32 v32, 0xbfb8aa3b, v31
	v_exp_f32_e32 v32, v32
	v_mul_f32_e32 v21, v28, v21
	v_add_f32_e32 v28, 1.0, v29
	v_rcp_f32_e32 v28, v28
	v_add_f32_e32 v29, 1.0, v32
	v_rcp_f32_e32 v29, v29
	v_cvt_pk_bf16_f32 v20, v20, v21
	v_mul_f32_e32 v21, v30, v28
	v_mul_f32_e32 v28, 0xbfb8aa3b, v24
	v_exp_f32_e32 v28, v28
	v_mul_f32_e32 v21, v21, v22
	v_mul_f32_e32 v22, v31, v29
	v_mul_f32_e32 v29, 0xbfb8aa3b, v25
	v_exp_f32_e32 v29, v29
	v_mul_f32_e32 v22, v22, v23
	v_add_f32_e32 v23, 1.0, v28
	v_rcp_f32_e32 v23, v23
	v_add_f32_e32 v28, 1.0, v29
	v_rcp_f32_e32 v28, v28
	v_cvt_pk_bf16_f32 v21, v21, v22
	v_mul_f32_e32 v22, v24, v23
	v_mul_f32_e32 v23, 0xbfb8aa3b, v26
	v_exp_f32_e32 v23, v23
	v_mul_f32_e32 v24, 0xbfb8aa3b, v27
	v_exp_f32_e32 v24, v24
	v_mul_f32_e32 v16, v22, v16
	v_mul_f32_e32 v22, v25, v28
	v_mul_f32_e32 v17, v22, v17
	v_add_f32_e32 v22, 1.0, v23
	v_rcp_f32_e32 v23, v22
	v_add_f32_e32 v22, 1.0, v24
	v_rcp_f32_e32 v24, v22
	v_cvt_pk_bf16_f32 v22, v16, v17
	v_mul_f32_e32 v16, v26, v23
	v_mul_f32_e32 v16, v16, v18
	v_mul_f32_e32 v17, v27, v24
	v_mul_f32_e32 v18, 0xbfb8aa3b, v12
	v_mul_f32_e32 v17, v17, v19
	v_exp_f32_e32 v18, v18
	v_mul_f32_e32 v19, 0xbfb8aa3b, v13
	v_exp_f32_e32 v19, v19
	v_cvt_pk_bf16_f32 v23, v16, v17
	v_add_f32_e32 v18, 1.0, v18
	v_rcp_f32_e32 v18, v18
	v_add_f32_e32 v19, 1.0, v19
	v_rcp_f32_e32 v19, v19
	v_add_u32_e32 v16, 0xa0, v150
	v_mul_f32_e32 v12, v12, v18
	v_mul_f32_e32 v4, v12, v4
	v_mul_f32_e32 v12, v13, v19
	v_mul_f32_e32 v13, 0xbfb8aa3b, v14
	v_exp_f32_e32 v13, v13
	v_mad_i64_i32 v[16:17], s[14:15], v16, s42, v[112:113]
	v_lshl_add_u64 v[16:17], v[16:17], 0, v[114:115]
	global_store_dwordx4 v[16:17], v[20:23], off
	v_mul_f32_e32 v16, 0xbfb8aa3b, v15
	v_exp_f32_e32 v16, v16
	v_mul_f32_e32 v5, v12, v5
	v_add_f32_e32 v12, 1.0, v13
	v_rcp_f32_e32 v12, v12
	v_add_f32_e32 v13, 1.0, v16
	v_rcp_f32_e32 v13, v13
	v_cvt_pk_bf16_f32 v4, v4, v5
	v_mul_f32_e32 v5, v14, v12
	v_mul_f32_e32 v12, 0xbfb8aa3b, v8
	v_exp_f32_e32 v12, v12
	v_mul_f32_e32 v5, v5, v6
	v_mul_f32_e32 v6, v15, v13
	v_mul_f32_e32 v13, 0xbfb8aa3b, v9
	v_exp_f32_e32 v13, v13
	v_mul_f32_e32 v6, v6, v7
	v_add_f32_e32 v7, 1.0, v12
	v_rcp_f32_e32 v7, v7
	v_add_f32_e32 v12, 1.0, v13
	v_rcp_f32_e32 v12, v12
	v_cvt_pk_bf16_f32 v5, v5, v6
	v_mul_f32_e32 v6, v8, v7
	v_mul_f32_e32 v7, 0xbfb8aa3b, v10
	v_exp_f32_e32 v7, v7
	v_mul_f32_e32 v8, 0xbfb8aa3b, v11
	v_exp_f32_e32 v8, v8
	v_mul_f32_e32 v0, v6, v0
	v_mul_f32_e32 v6, v9, v12
	v_mul_f32_e32 v1, v6, v1
	v_add_f32_e32 v6, 1.0, v7
	v_rcp_f32_e32 v7, v6
	v_add_f32_e32 v6, 1.0, v8
	v_rcp_f32_e32 v8, v6
	v_cvt_pk_bf16_f32 v6, v0, v1
	v_mul_f32_e32 v0, v10, v7
	v_mul_f32_e32 v0, v0, v2
	v_mul_f32_e32 v1, v11, v8
	v_mul_f32_e32 v1, v1, v3
	v_cvt_pk_bf16_f32 v7, v0, v1
	v_add_u32_e32 v0, 0xb0, v150
	v_mad_i64_i32 v[0:1], s[14:15], v0, s42, v[112:113]
	v_lshl_add_u64 v[0:1], v[0:1], 0, v[114:115]
	s_and_b64 vcc, exec, s[2:3]
	s_mov_b32 s43, s4
	s_mov_b32 s12, s6
	s_mov_b64 s[18:19], s[10:11]
	s_mov_b64 s[14:15], s[8:9]
	global_store_dwordx4 v[0:1], v[4:7], off
	s_barrier
	s_cbranch_vccz .LBB0_232
.Lconc_end_g0:
	s_waitcnt vmcnt(0)
	s_cmpk_gt_u32 s24, 0xff
	s_cbranch_scc1 .LBB0_239
	s_barrier

; #define PG8_STAGE(bufoff, gbase, voff) do { _Pragma("unroll") for (int _i = 0; _i < 2; ++_i) \
;         __builtin_amdgcn_global_load_lds((const unsigned*)((const char*)(gbase) + (voff)[_i]), (LAS unsigned*)(lds + (bufoff) + ldsw + _i * 8192), 16, 0, 0); } while (0)
; #define PG8_LDA(dst, b, h) do { _Pragma("unroll") for (int m = 0; m < 4; ++m) _Pragma("unroll") for (int k = 0; k < 2; ++k) dst[m][k] = *(const LAS bf16x8*)(lds + PG8_SA(b, h) + aoff + m * 2048 + k * 1024); } while (0)
; #define PG8_LDB(dst, b, h) do { _Pragma("unroll") for (int n = 0; n < 2; ++n) _Pragma("unroll") for (int k = 0; k < 2; ++k) dst[n][k] = *(const LAS bf16x8*)(lds + PG8_SB(b, h) + boff + n * 2048 + k * 1024); } while (0)
; #define PG8_MMA(ai, bj, At, Bt) do { __builtin_amdgcn_s_setprio(1); _Pragma("unroll") for (int m = 0; m < 4; ++m) _Pragma("unroll") for (int n = 0; n < 2; ++n) _Pragma("unroll") for (int k = 0; k < 2; ++k) \
;         acc[ai][bj][m][n] = __builtin_amdgcn_mfma_f32_16x16x32_bf16(Bt[n][k], At[m][k], acc[ai][bj][m][n], 0, 0, 0); __builtin_amdgcn_s_setprio(0); } while (0)
; #define PG8_WAIT_L(n) asm volatile("s_waitcnt lgkmcnt(" #n ")" ::: "memory")
; #define PG8_BAR __builtin_amdgcn_s_barrier()
; #define PG8_SCHED __builtin_amdgcn_sched_barrier(0)
; template <class Epi, class Sched>
; __device__ __forceinline__ void gemm_phase(LAS unsigned char* lds, const Gemm g, const Sched& S, const Epi& E) {
;     ...
;         for (int t = 0; t < nt; t += 2) {
;             const bool last = (t == nt - 2);
;             const char* a1 = cA + (size_t)(t + 1) * kstep;
;             const char* a2 = last ? nA : cA + (size_t)(t + 2) * kstep; const char* b2 = last ? nB : cB + (size_t)(t + 2) * kstep;
;             const char* a3 = a2 + kstep; const char* b3 = b2 + kstep;
;             PG8_LDB(B0, 0, 0); PG8_SCHED; PG8_LDA(At, 0, 0); PG8_STAGE(PG8_SA(1, 1), a1 + hstep, voffA);
;             PG8_WAIT_L(8); PG8_BAR; PG8_WAIT_L(0); PG8_MMA(0, 0, At, B0); PG8_BAR; PG8_SCHED;
;             PG8_LDB(B1, 0, 1); PG8_STAGE(PG8_SB(0, 0), b2, voffB);
;             PG8_BAR; PG8_WAIT_L(0); PG8_MMA(0, 1, At, B1); PG8_BAR;
;             PG8_LDA(At, 0, 1); PG8_STAGE(PG8_SA(0, 0), a2, voffA);
;             PG8_BAR; PG8_WAIT_L(0); PG8_MMA(1, 0, At, B0); PG8_BAR; PG8_SCHED;
.LBB0_1021:
	ds_read_b128 v[150:153], v147
	ds_read_b128 v[154:157], v147 offset:1024
	ds_read_b128 v[158:161], v147 offset:2048
	ds_read_b128 v[162:165], v147 offset:3072
	s_add_u32 s18, s16, 0xfffc0080
	s_addc_u32 s19, s17, -1
	s_cmp_eq_u32 s46, 12
	s_cselect_b32 s21, s7, s19
	s_cselect_b32 s20, s42, s18
	s_cselect_b32 s19, s5, s45
	s_cselect_b32 s18, s43, s44
	s_add_i32 m0, s15, 0xc000
	ds_read_b128 v[166:169], v148
	ds_read_b128 v[170:173], v148 offset:1024
	ds_read_b128 v[174:177], v148 offset:2048
	ds_read_b128 v[178:181], v148 offset:3072
	ds_read_b128 v[182:185], v148 offset:4096
	ds_read_b128 v[186:189], v148 offset:5120
	ds_read_b128 v[190:193], v148 offset:6144
	ds_read_b128 v[194:197], v148 offset:7168
	global_load_lds_dwordx4 v136, s[16:17]
	s_add_i32 m0, s15, 0xe000
	s_nop 0
	global_load_lds_dwordx4 v138, s[16:17]
	s_waitcnt lgkmcnt(8)
	s_waitcnt vmcnt(10)
	s_barrier
	s_waitcnt lgkmcnt(0)
	s_setprio 1
	s_waitcnt lgkmcnt(0)
	v_mfma_f32_16x16x32_bf16 v[124:127], v[150:153], v[166:169], v[124:127]
	v_mfma_f32_16x16x32_bf16 v[116:119], v[158:161], v[166:169], v[116:119]
	v_mfma_f32_16x16x32_bf16 v[108:111], v[150:153], v[174:177], v[108:111]
	v_mfma_f32_16x16x32_bf16 v[100:103], v[158:161], v[174:177], v[100:103]
	v_mfma_f32_16x16x32_bf16 v[92:95], v[150:153], v[182:185], v[92:95]
	v_mfma_f32_16x16x32_bf16 v[84:87], v[158:161], v[182:185], v[84:87]
	v_mfma_f32_16x16x32_bf16 v[76:79], v[150:153], v[190:193], v[76:79]
	v_mfma_f32_16x16x32_bf16 v[68:71], v[158:161], v[190:193], v[68:71]
	v_mfma_f32_16x16x32_bf16 v[124:127], v[154:157], v[170:173], v[124:127]
	v_mfma_f32_16x16x32_bf16 v[116:119], v[162:165], v[170:173], v[116:119]
	v_mfma_f32_16x16x32_bf16 v[108:111], v[154:157], v[178:181], v[108:111]
	v_mfma_f32_16x16x32_bf16 v[100:103], v[162:165], v[178:181], v[100:103]
	v_mfma_f32_16x16x32_bf16 v[92:95], v[154:157], v[186:189], v[92:95]
	v_mfma_f32_16x16x32_bf16 v[84:87], v[162:165], v[186:189], v[84:87]
	v_mfma_f32_16x16x32_bf16 v[76:79], v[154:157], v[194:197], v[76:79]
	v_mfma_f32_16x16x32_bf16 v[68:71], v[162:165], v[194:197], v[68:71]
	s_setprio 0
	s_barrier
	s_add_i32 s47, s38, s25
	s_mov_b32 m0, s47
	ds_read_b128 v[202:205], v149
	ds_read_b128 v[206:209], v149 offset:1024
	ds_read_b128 v[210:213], v149 offset:2048
	ds_read_b128 v[214:217], v149 offset:3072
	global_load_lds_dwordx4 v132, s[18:19]
	s_add_i32 m0, s47, 0x2000
	s_nop 0
	global_load_lds_dwordx4 v128, s[18:19]
	s_waitcnt vmcnt(10)
	s_barrier
	s_waitcnt lgkmcnt(0)
	s_setprio 1
	s_waitcnt lgkmcnt(0)
	v_mfma_f32_16x16x32_bf16 v[120:123], v[202:205], v[166:169], v[120:123]
	v_mfma_f32_16x16x32_bf16 v[112:115], v[210:213], v[166:169], v[112:115]
	v_mfma_f32_16x16x32_bf16 v[104:107], v[202:205], v[174:177], v[104:107]
	v_mfma_f32_16x16x32_bf16 v[96:99], v[210:213], v[174:177], v[96:99]
	v_mfma_f32_16x16x32_bf16 v[88:91], v[202:205], v[182:185], v[88:91]
	v_mfma_f32_16x16x32_bf16 v[80:83], v[210:213], v[182:185], v[80:83]
	v_mfma_f32_16x16x32_bf16 v[72:75], v[202:205], v[190:193], v[72:75]
	v_mfma_f32_16x16x32_bf16 v[64:67], v[210:213], v[190:193], v[64:67]
	v_mfma_f32_16x16x32_bf16 v[120:123], v[206:209], v[170:173], v[120:123]
	v_mfma_f32_16x16x32_bf16 v[112:115], v[214:217], v[170:173], v[112:115]
	v_mfma_f32_16x16x32_bf16 v[104:107], v[206:209], v[178:181], v[104:107]
	v_mfma_f32_16x16x32_bf16 v[96:99], v[214:217], v[178:181], v[96:99]
	v_mfma_f32_16x16x32_bf16 v[88:91], v[206:209], v[186:189], v[88:91]
	v_mfma_f32_16x16x32_bf16 v[80:83], v[214:217], v[186:189], v[80:83]
	v_mfma_f32_16x16x32_bf16 v[72:75], v[206:209], v[194:197], v[72:75]
	v_mfma_f32_16x16x32_bf16 v[64:67], v[214:217], v[194:197], v[64:67]
	s_setprio 0
	s_mov_b32 m0, s15
	v_lshl_add_u64 v[220:221], s[20:21], 0, v[134:135]
	s_barrier
	ds_read_b128 v[166:169], v148 offset:16384
	ds_read_b128 v[170:173], v148 offset:17408
	ds_read_b128 v[174:177], v148 offset:18432
	ds_read_b128 v[178:181], v148 offset:19456
	ds_read_b128 v[182:185], v148 offset:20480
	ds_read_b128 v[186:189], v148 offset:21504
	ds_read_b128 v[190:193], v148 offset:22528
	ds_read_b128 v[194:197], v148 offset:23552
	global_load_lds_dwordx4 v134, s[20:21]
	v_lshl_add_u64 v[222:223], s[20:21], 0, v[130:131]
	s_mov_b32 m0, s28
	s_nop 0
	global_load_lds_dwordx4 v130, s[20:21]
	s_barrier
	s_waitcnt lgkmcnt(0)
	s_setprio 1
	s_waitcnt lgkmcnt(0)
	v_mfma_f32_16x16x32_bf16 v[60:63], v[150:153], v[166:169], v[60:63]
	v_mfma_f32_16x16x32_bf16 v[56:59], v[158:161], v[166:169], v[56:59]
	v_mfma_f32_16x16x32_bf16 v[44:47], v[150:153], v[174:177], v[44:47]
	v_mfma_f32_16x16x32_bf16 v[40:43], v[158:161], v[174:177], v[40:43]
	v_mfma_f32_16x16x32_bf16 v[28:31], v[150:153], v[182:185], v[28:31]
	v_mfma_f32_16x16x32_bf16 v[24:27], v[158:161], v[182:185], v[24:27]
	v_mfma_f32_16x16x32_bf16 v[12:15], v[150:153], v[190:193], v[12:15]
	v_mfma_f32_16x16x32_bf16 v[8:11], v[158:161], v[190:193], v[8:11]
	v_mfma_f32_16x16x32_bf16 v[60:63], v[154:157], v[170:173], v[60:63]
	v_mfma_f32_16x16x32_bf16 v[56:59], v[162:165], v[170:173], v[56:59]
	v_mfma_f32_16x16x32_bf16 v[44:47], v[154:157], v[178:181], v[44:47]
	v_mfma_f32_16x16x32_bf16 v[40:43], v[162:165], v[178:181], v[40:43]
	v_mfma_f32_16x16x32_bf16 v[28:31], v[154:157], v[186:189], v[28:31]
	v_mfma_f32_16x16x32_bf16 v[24:27], v[162:165], v[186:189], v[24:27]
	v_mfma_f32_16x16x32_bf16 v[12:15], v[154:157], v[194:197], v[12:15]
	v_mfma_f32_16x16x32_bf16 v[8:11], v[162:165], v[194:197], v[8:11]
	s_setprio 0
	s_barrier
; #define PG8_STAGE(bufoff, gbase, voff) do { _Pragma("unroll") for (int _i = 0; _i < 2; ++_i) \
;         __builtin_amdgcn_global_load_lds((const unsigned*)((const char*)(gbase) + (voff)[_i]), (LAS unsigned*)(lds + (bufoff) + ldsw + _i * 8192), 16, 0, 0); } while (0)
; #define PG8_LDA(dst, b, h) do { _Pragma("unroll") for (int m = 0; m < 4; ++m) _Pragma("unroll") for (int k = 0; k < 2; ++k) dst[m][k] = *(const LAS bf16x8*)(lds + PG8_SA(b, h) + aoff + m * 2048 + k * 1024); } while (0)
; #define PG8_LDB(dst, b, h) do { _Pragma("unroll") for (int n = 0; n < 2; ++n) _Pragma("unroll") for (int k = 0; k < 2; ++k) dst[n][k] = *(const LAS bf16x8*)(lds + PG8_SB(b, h) + boff + n * 2048 + k * 1024); } while (0)
; #define PG8_MMA(ai, bj, At, Bt) do { __builtin_amdgcn_s_setprio(1); _Pragma("unroll") for (int m = 0; m < 4; ++m) _Pragma("unroll") for (int n = 0; n < 2; ++n) _Pragma("unroll") for (int k = 0; k < 2; ++k) \
;         acc[ai][bj][m][n] = __builtin_amdgcn_mfma_f32_16x16x32_bf16(Bt[n][k], At[m][k], acc[ai][bj][m][n], 0, 0, 0); __builtin_amdgcn_s_setprio(0); } while (0)
; #define PG8_WAIT_V(n) asm volatile("s_waitcnt vmcnt(" #n ")" ::: "memory")
; #define PG8_WAIT_L(n) asm volatile("s_waitcnt lgkmcnt(" #n ")" ::: "memory")
; #define PG8_BAR __builtin_amdgcn_s_barrier()
; #define PG8_SCHED __builtin_amdgcn_sched_barrier(0)
; template <class Epi, class Sched>
; __device__ __forceinline__ void gemm_phase(LAS unsigned char* lds, const Gemm g, const Sched& S, const Epi& E) {
;     ...
;             PG8_STAGE(PG8_SB(0, 1), b2 + hstep, voffB);
;             PG8_WAIT_V(6); PG8_BAR; PG8_MMA(1, 1, At, B1); PG8_BAR;
;             PG8_LDB(B0, 1, 0); PG8_SCHED; PG8_LDA(At, 1, 0); PG8_STAGE(PG8_SA(0, 1), a2 + hstep, voffA);
;             PG8_WAIT_L(8); PG8_BAR; PG8_WAIT_L(0); PG8_MMA(0, 0, At, B0); PG8_BAR; PG8_SCHED;
;             PG8_LDB(B1, 1, 1); PG8_STAGE(PG8_SB(1, 0), b3, voffB);
;             PG8_BAR; PG8_WAIT_L(0); PG8_MMA(0, 1, At, B1); PG8_BAR;
;             PG8_LDA(At, 1, 1); PG8_STAGE(PG8_SA(1, 0), a3, voffA);
;             PG8_BAR; PG8_WAIT_L(0); PG8_MMA(1, 0, At, B0); PG8_BAR; PG8_SCHED;
	s_add_u32 s48, s18, 0x40000
	s_addc_u32 s49, s19, 0
	s_add_i32 s47, s39, s25
	s_mov_b32 m0, s47
	s_nop 0
	global_load_lds_dwordx4 v132, s[48:49]
	s_add_i32 m0, s47, 0x2000
	s_nop 0
	global_load_lds_dwordx4 v128, s[48:49]
	s_add_u32 s20, s20, 0x40000
	s_addc_u32 s21, s21, 0
	s_mov_b32 m0, s29
	s_nop 0
	global_load_lds_dwordx4 v134, s[20:21]
	s_mov_b32 m0, s30
	s_nop 0
	global_load_lds_dwordx4 v130, s[20:21]
	s_waitcnt vmcnt(12)
	s_barrier
	s_setprio 1
	v_mfma_f32_16x16x32_bf16 v[52:55], v[202:205], v[166:169], v[52:55]
	v_mfma_f32_16x16x32_bf16 v[48:51], v[210:213], v[166:169], v[48:51]
	v_mfma_f32_16x16x32_bf16 v[36:39], v[202:205], v[174:177], v[36:39]
	v_mfma_f32_16x16x32_bf16 v[32:35], v[210:213], v[174:177], v[32:35]
	v_mfma_f32_16x16x32_bf16 v[20:23], v[202:205], v[182:185], v[20:23]
	v_mfma_f32_16x16x32_bf16 v[16:19], v[210:213], v[182:185], v[16:19]
	v_mfma_f32_16x16x32_bf16 v[4:7], v[202:205], v[190:193], v[4:7]
	v_mfma_f32_16x16x32_bf16 v[0:3], v[210:213], v[190:193], v[0:3]
	v_mfma_f32_16x16x32_bf16 v[52:55], v[206:209], v[170:173], v[52:55]
	v_mfma_f32_16x16x32_bf16 v[48:51], v[214:217], v[170:173], v[48:51]
	v_mfma_f32_16x16x32_bf16 v[36:39], v[206:209], v[178:181], v[36:39]
	v_mfma_f32_16x16x32_bf16 v[32:35], v[214:217], v[178:181], v[32:35]
	v_mfma_f32_16x16x32_bf16 v[20:23], v[206:209], v[186:189], v[20:23]
	v_mfma_f32_16x16x32_bf16 v[16:19], v[214:217], v[186:189], v[16:19]
	v_mfma_f32_16x16x32_bf16 v[4:7], v[206:209], v[194:197], v[4:7]
	v_mfma_f32_16x16x32_bf16 v[0:3], v[214:217], v[194:197], v[0:3]
	s_setprio 0
	s_add_i32 s47, 0, 0x18000
	v_add_u32_e32 v162, s47, v146
	s_barrier
	ds_read_b128 v[150:153], v162
	ds_read_b128 v[154:157], v162 offset:1024
	ds_read_b128 v[158:161], v162 offset:2048
	ds_read_b128 v[162:165], v162 offset:3072
	ds_read_b128 v[166:169], v148 offset:32768
	ds_read_b128 v[170:173], v148 offset:33792
	ds_read_b128 v[174:177], v148 offset:34816
	ds_read_b128 v[178:181], v148 offset:35840
	ds_read_b128 v[182:185], v148 offset:36864
	ds_read_b128 v[186:189], v148 offset:37888
	ds_read_b128 v[190:193], v148 offset:38912
	ds_read_b128 v[194:197], v148 offset:39936
	s_waitcnt lgkmcnt(8)
	s_waitcnt vmcnt(10)
	s_barrier
	s_waitcnt lgkmcnt(0)
	s_setprio 1
	s_waitcnt lgkmcnt(0)
	v_mfma_f32_16x16x32_bf16 v[124:127], v[150:153], v[166:169], v[124:127]
	v_mfma_f32_16x16x32_bf16 v[116:119], v[158:161], v[166:169], v[116:119]
	v_mfma_f32_16x16x32_bf16 v[108:111], v[150:153], v[174:177], v[108:111]
	v_mfma_f32_16x16x32_bf16 v[100:103], v[158:161], v[174:177], v[100:103]
	v_mfma_f32_16x16x32_bf16 v[92:95], v[150:153], v[182:185], v[92:95]
	v_mfma_f32_16x16x32_bf16 v[84:87], v[158:161], v[182:185], v[84:87]
	v_mfma_f32_16x16x32_bf16 v[76:79], v[150:153], v[190:193], v[76:79]
	v_mfma_f32_16x16x32_bf16 v[68:71], v[158:161], v[190:193], v[68:71]
	v_mfma_f32_16x16x32_bf16 v[124:127], v[154:157], v[170:173], v[124:127]
	v_mfma_f32_16x16x32_bf16 v[116:119], v[162:165], v[170:173], v[116:119]
	v_mfma_f32_16x16x32_bf16 v[108:111], v[154:157], v[178:181], v[108:111]
	v_mfma_f32_16x16x32_bf16 v[100:103], v[162:165], v[178:181], v[100:103]
	v_mfma_f32_16x16x32_bf16 v[92:95], v[154:157], v[186:189], v[92:95]
	v_mfma_f32_16x16x32_bf16 v[84:87], v[162:165], v[186:189], v[84:87]
	v_mfma_f32_16x16x32_bf16 v[76:79], v[154:157], v[194:197], v[76:79]
	v_mfma_f32_16x16x32_bf16 v[68:71], v[162:165], v[194:197], v[68:71]
	s_setprio 0
	s_barrier
	s_add_i32 s20, 0, 0x1c000
	s_add_i32 s21, s47, s25
	v_add_u32_e32 v214, s20, v146
	s_add_u32 s0, s18, 0x80
	s_addc_u32 s1, s19, 0
	s_mov_b32 m0, s21
	ds_read_b128 v[202:205], v214
	ds_read_b128 v[206:209], v214 offset:1024
	ds_read_b128 v[210:213], v214 offset:2048
	ds_read_b128 v[214:217], v214 offset:3072
	global_load_lds_dwordx4 v132, s[0:1]
	s_add_i32 m0, s21, 0x2000
	s_nop 0
	global_load_lds_dwordx4 v128, s[0:1]
	s_waitcnt vmcnt(10)
	s_barrier
	s_waitcnt lgkmcnt(0)
	s_setprio 1
	s_waitcnt lgkmcnt(0)
	v_mfma_f32_16x16x32_bf16 v[120:123], v[202:205], v[166:169], v[120:123]
	v_mfma_f32_16x16x32_bf16 v[112:115], v[210:213], v[166:169], v[112:115]
	v_mfma_f32_16x16x32_bf16 v[104:107], v[202:205], v[174:177], v[104:107]
	v_mfma_f32_16x16x32_bf16 v[96:99], v[210:213], v[174:177], v[96:99]
	v_mfma_f32_16x16x32_bf16 v[88:91], v[202:205], v[182:185], v[88:91]
	v_mfma_f32_16x16x32_bf16 v[80:83], v[210:213], v[182:185], v[80:83]
	v_mfma_f32_16x16x32_bf16 v[72:75], v[202:205], v[190:193], v[72:75]
	v_mfma_f32_16x16x32_bf16 v[64:67], v[210:213], v[190:193], v[64:67]
	v_mfma_f32_16x16x32_bf16 v[120:123], v[206:209], v[170:173], v[120:123]
	v_mfma_f32_16x16x32_bf16 v[112:115], v[214:217], v[170:173], v[112:115]
	v_mfma_f32_16x16x32_bf16 v[104:107], v[206:209], v[178:181], v[104:107]
	v_mfma_f32_16x16x32_bf16 v[96:99], v[214:217], v[178:181], v[96:99]
	v_mfma_f32_16x16x32_bf16 v[88:91], v[206:209], v[186:189], v[88:91]
	v_mfma_f32_16x16x32_bf16 v[80:83], v[214:217], v[186:189], v[80:83]
	v_mfma_f32_16x16x32_bf16 v[72:75], v[206:209], v[194:197], v[72:75]
	v_mfma_f32_16x16x32_bf16 v[64:67], v[214:217], v[194:197], v[64:67]
	s_setprio 0
	s_mov_b32 m0, s35
	s_mov_b64 s[0:1], 0x80
	v_lshl_add_u64 v[198:199], v[220:221], 0, s[0:1]
	s_barrier
	ds_read_b128 v[166:169], v148 offset:49152
	ds_read_b128 v[170:173], v148 offset:50176
	ds_read_b128 v[174:177], v148 offset:51200
	ds_read_b128 v[178:181], v148 offset:52224
	ds_read_b128 v[182:185], v148 offset:53248
	ds_read_b128 v[186:189], v148 offset:54272
	ds_read_b128 v[190:193], v148 offset:55296
	ds_read_b128 v[194:197], v148 offset:56320
	global_load_lds_dwordx4 v[198:199], off
	v_lshl_add_u64 v[198:199], v[222:223], 0, s[0:1]
	s_mov_b32 m0, s36
	s_nop 0
	global_load_lds_dwordx4 v[198:199], off
	s_barrier
; __device__ __forceinline__ unsigned cvt_pk_bf16(float lo, float hi) { unsigned r; asm volatile("v_cvt_pk_bf16_f32 %0, %1, %2" : "=v"(r) : "v"(lo), "v"(hi)); return r; }
; __device__ __forceinline__ float silu_f(float a) { return a * __builtin_amdgcn_rcpf(1.0f + __expf(-a)); }
; #define PG8_MMA(ai, bj, At, Bt) do { __builtin_amdgcn_s_setprio(1); _Pragma("unroll") for (int m = 0; m < 4; ++m) _Pragma("unroll") for (int n = 0; n < 2; ++n) _Pragma("unroll") for (int k = 0; k < 2; ++k) \
;         acc[ai][bj][m][n] = __builtin_amdgcn_mfma_f32_16x16x32_bf16(Bt[n][k], At[m][k], acc[ai][bj][m][n], 0, 0, 0); __builtin_amdgcn_s_setprio(0); } while (0)
; #define PG8_WAIT_V(n) asm volatile("s_waitcnt vmcnt(" #n ")" ::: "memory")
; #define PG8_BAR __builtin_amdgcn_s_barrier()
; template <class Epi, class Sched>
; __device__ __forceinline__ void gemm_phase(LAS unsigned char* lds, const Gemm g, const Sched& S, const Epi& E) {
;     ...
;             PG8_WAIT_V(6); PG8_BAR; PG8_MMA(1, 1, At, B1); PG8_BAR;
;         }
;         E(acc, cur, wr, wc, fr, fq);
;     __device__ __forceinline__ void operator()(const AccT& acc, const Unit& u, int wr, int wc, int fr, int fq) const {
;     ...
;         const int row0 = u.pm * 256 + wr * 64 + fr, hc0 = u.pn * 128 + wc * 32 + 8 * fq;
; #pragma unroll
;         for (int ai = 0; ai < 2; ++ai)
; #pragma unroll
;             for (int m = 0; m < 4; ++m) {
;                 const f32x4 a0 = acc[ai][0][m][0], a1 = acc[ai][0][m][1], b0 = acc[ai][1][m][0], b1 = acc[ai][1][m][1];
;                 u32x4 w;
;                 w.x = cvt_pk_bf16(silu_f(a0[0]) * b0[0], silu_f(a0[1]) * b0[1]); w.y = cvt_pk_bf16(silu_f(a0[2]) * b0[2], silu_f(a0[3]) * b0[3]);
;                 w.z = cvt_pk_bf16(silu_f(a1[0]) * b1[0], silu_f(a1[1]) * b1[1]); w.w = cvt_pk_bf16(silu_f(a1[2]) * b1[2], silu_f(a1[3]) * b1[3]);
;                 *(u32x4*)(H + (size_t)(row0 + ai * 128 + m * 16) * DFF + hc0) = w;
	s_waitcnt lgkmcnt(0)
	s_setprio 1
	s_waitcnt lgkmcnt(0)
	v_mfma_f32_16x16x32_bf16 v[60:63], v[150:153], v[166:169], v[60:63]
	v_mfma_f32_16x16x32_bf16 v[56:59], v[158:161], v[166:169], v[56:59]
	v_mfma_f32_16x16x32_bf16 v[44:47], v[150:153], v[174:177], v[44:47]
	v_mfma_f32_16x16x32_bf16 v[40:43], v[158:161], v[174:177], v[40:43]
	v_mfma_f32_16x16x32_bf16 v[28:31], v[150:153], v[182:185], v[28:31]
	v_mfma_f32_16x16x32_bf16 v[24:27], v[158:161], v[182:185], v[24:27]
	v_mfma_f32_16x16x32_bf16 v[12:15], v[150:153], v[190:193], v[12:15]
	v_mfma_f32_16x16x32_bf16 v[8:11], v[158:161], v[190:193], v[8:11]
	v_mfma_f32_16x16x32_bf16 v[60:63], v[154:157], v[170:173], v[60:63]
	v_mfma_f32_16x16x32_bf16 v[56:59], v[162:165], v[170:173], v[56:59]
	v_mfma_f32_16x16x32_bf16 v[44:47], v[154:157], v[178:181], v[44:47]
	v_mfma_f32_16x16x32_bf16 v[40:43], v[162:165], v[178:181], v[40:43]
	v_mfma_f32_16x16x32_bf16 v[28:31], v[154:157], v[186:189], v[28:31]
	v_mfma_f32_16x16x32_bf16 v[24:27], v[162:165], v[186:189], v[24:27]
	v_mfma_f32_16x16x32_bf16 v[12:15], v[154:157], v[194:197], v[12:15]
	v_mfma_f32_16x16x32_bf16 v[8:11], v[162:165], v[194:197], v[8:11]
	s_setprio 0
	s_barrier
	s_add_u32 s18, s18, 0x40080
	s_addc_u32 s19, s19, 0
	s_add_i32 s20, s20, s25
	s_mov_b32 m0, s20
	s_nop 0
	global_load_lds_dwordx4 v132, s[18:19]
	s_add_i32 m0, s20, 0x2000
	s_nop 0
	global_load_lds_dwordx4 v128, s[18:19]
	s_waitcnt vmcnt(10)
	s_barrier
	s_setprio 1
	v_mfma_f32_16x16x32_bf16 v[52:55], v[202:205], v[166:169], v[52:55]
	v_mfma_f32_16x16x32_bf16 v[48:51], v[210:213], v[166:169], v[48:51]
	v_mfma_f32_16x16x32_bf16 v[36:39], v[202:205], v[174:177], v[36:39]
	v_mfma_f32_16x16x32_bf16 v[32:35], v[210:213], v[174:177], v[32:35]
	v_mfma_f32_16x16x32_bf16 v[20:23], v[202:205], v[182:185], v[20:23]
	v_mfma_f32_16x16x32_bf16 v[16:19], v[210:213], v[182:185], v[16:19]
	v_mfma_f32_16x16x32_bf16 v[4:7], v[202:205], v[190:193], v[4:7]
	v_mfma_f32_16x16x32_bf16 v[0:3], v[210:213], v[190:193], v[0:3]
	v_mfma_f32_16x16x32_bf16 v[52:55], v[206:209], v[170:173], v[52:55]
	v_mfma_f32_16x16x32_bf16 v[48:51], v[214:217], v[170:173], v[48:51]
	v_mfma_f32_16x16x32_bf16 v[36:39], v[206:209], v[178:181], v[36:39]
	v_mfma_f32_16x16x32_bf16 v[32:35], v[214:217], v[178:181], v[32:35]
	v_mfma_f32_16x16x32_bf16 v[20:23], v[206:209], v[186:189], v[20:23]
	v_mfma_f32_16x16x32_bf16 v[16:19], v[214:217], v[186:189], v[16:19]
	v_mfma_f32_16x16x32_bf16 v[4:7], v[206:209], v[194:197], v[4:7]
	v_mfma_f32_16x16x32_bf16 v[0:3], v[214:217], v[194:197], v[0:3]
	s_setprio 0
	s_add_i32 s46, s46, 2
	s_add_u32 s16, s16, 0x100
	s_addc_u32 s17, s17, 0
	s_add_u32 s44, s44, 0x100
	s_addc_u32 s45, s45, 0
	s_cmp_gt_u32 s46, 13
	s_cbranch_scc1 .Lconc_last_g11
	s_barrier
	s_branch .LBB0_1021
.Lconc_last_g11:
	v_readfirstlane_b32 s5, v200
	s_nop 3
	s_cmp_gt_u32 s5, 0xff
	s_cbranch_scc1 .Lconc_epi1_g11
	s_barrier
	v_mul_f32_e32 v152, 0xbfb8aa3b, v124
	v_mov_b32_e32 v150, v144
	v_mov_b32_e32 v151, v145
	s_lshl_b32 s5, s14, 8
	v_exp_f32_e32 v153, v152
	v_mul_f32_e32 v152, 0xbfb8aa3b, v125
	s_add_i32 s5, s5, s33
	v_exp_f32_e32 v154, v152
	v_add_u32_e32 v150, s5, v150
	s_lshl_b32 s5, s41, 7
	s_or_b32 s5, s5, s34
	v_lshl_add_u32 v152, v151, 3, s5
	v_add_f32_e32 v151, 1.0, v153
	v_rcp_f32_e32 v151, v151
	v_add_f32_e32 v153, 1.0, v154
	v_rcp_f32_e32 v154, v153
	v_ashrrev_i32_e32 v153, 31, v152
	v_mul_f32_e32 v124, v124, v151
	v_mul_f32_e32 v120, v124, v120
	v_mul_f32_e32 v124, v125, v154
	v_mul_f32_e32 v125, 0xbfb8aa3b, v126
	v_exp_f32_e32 v125, v125
	v_mul_f32_e32 v151, 0xbfb8aa3b, v127
	v_exp_f32_e32 v151, v151
	v_mul_f32_e32 v121, v124, v121
	v_add_f32_e32 v124, 1.0, v125
	v_rcp_f32_e32 v124, v124
	v_add_f32_e32 v125, 1.0, v151
	v_rcp_f32_e32 v125, v125
	v_cvt_pk_bf16_f32 v120, v120, v121
	v_mul_f32_e32 v121, v126, v124
	v_mul_f32_e32 v124, 0xbfb8aa3b, v116
	v_mul_f32_e32 v121, v121, v122
	v_mul_f32_e32 v122, v127, v125
	v_exp_f32_e32 v124, v124
	v_mul_f32_e32 v125, 0xbfb8aa3b, v117
	v_exp_f32_e32 v125, v125
	v_mul_f32_e32 v122, v122, v123
	v_add_f32_e32 v123, 1.0, v124
	v_rcp_f32_e32 v123, v123
	v_add_f32_e32 v124, 1.0, v125
	v_rcp_f32_e32 v124, v124
	v_cvt_pk_bf16_f32 v121, v121, v122
	v_mul_f32_e32 v116, v116, v123
	v_mul_f32_e32 v112, v116, v112
	v_mul_f32_e32 v116, v117, v124
	v_mul_f32_e32 v117, 0xbfb8aa3b, v118
	v_exp_f32_e32 v117, v117
	v_mul_f32_e32 v122, 0xbfb8aa3b, v119
	v_exp_f32_e32 v122, v122
	v_mul_f32_e32 v113, v116, v113
	v_add_f32_e32 v116, 1.0, v117
	v_rcp_f32_e32 v116, v116
	v_add_f32_e32 v117, 1.0, v122
	v_rcp_f32_e32 v117, v117
	v_cvt_pk_bf16_f32 v122, v112, v113
	v_mul_f32_e32 v112, v118, v116
	v_mul_f32_e32 v118, 0xbfb8aa3b, v108
	v_mul_f32_e32 v113, v119, v117
	v_exp_f32_e32 v118, v118
	v_mul_f32_e32 v119, 0xbfb8aa3b, v109
	v_exp_f32_e32 v119, v119
	v_mul_f32_e32 v112, v112, v114
	v_add_f32_e32 v118, 1.0, v118
	v_rcp_f32_e32 v118, v118
	v_add_f32_e32 v119, 1.0, v119
	v_rcp_f32_e32 v119, v119
	v_mul_f32_e32 v113, v113, v115
	v_cvt_pk_bf16_f32 v123, v112, v113
	v_mov_b64_e32 v[112:113], s[82:83]
	v_mad_i64_i32 v[116:117], s[16:17], v150, s40, v[112:113]
	v_lshlrev_b64 v[114:115], 1, v[152:153]
	v_mul_f32_e32 v108, v108, v118
	v_lshl_add_u64 v[116:117], v[116:117], 0, v[114:115]
	v_mul_f32_e32 v104, v108, v104
	v_mul_f32_e32 v108, v109, v119
	v_mul_f32_e32 v109, 0xbfb8aa3b, v110
	global_store_dwordx4 v[116:117], v[120:123], off
	v_exp_f32_e32 v109, v109
	v_mul_f32_e32 v116, 0xbfb8aa3b, v111
	v_exp_f32_e32 v116, v116
	v_mul_f32_e32 v105, v108, v105
	v_add_f32_e32 v108, 1.0, v109
	v_rcp_f32_e32 v108, v108
	v_add_f32_e32 v109, 1.0, v116
	v_rcp_f32_e32 v109, v109
	v_cvt_pk_bf16_f32 v104, v104, v105
; __device__ __forceinline__ unsigned cvt_pk_bf16(float lo, float hi) { unsigned r; asm volatile("v_cvt_pk_bf16_f32 %0, %1, %2" : "=v"(r) : "v"(lo), "v"(hi)); return r; }
; __device__ __forceinline__ float silu_f(float a) { return a * __builtin_amdgcn_rcpf(1.0f + __expf(-a)); }
;     __device__ __forceinline__ void operator()(const AccT& acc, const Unit& u, int wr, int wc, int fr, int fq) const {
;     ...
;         const int row0 = u.pm * 256 + wr * 64 + fr, hc0 = u.pn * 128 + wc * 32 + 8 * fq;
; #pragma unroll
;         for (int ai = 0; ai < 2; ++ai)
; #pragma unroll
;             for (int m = 0; m < 4; ++m) {
;                 const f32x4 a0 = acc[ai][0][m][0], a1 = acc[ai][0][m][1], b0 = acc[ai][1][m][0], b1 = acc[ai][1][m][1];
;                 u32x4 w;
;                 w.x = cvt_pk_bf16(silu_f(a0[0]) * b0[0], silu_f(a0[1]) * b0[1]); w.y = cvt_pk_bf16(silu_f(a0[2]) * b0[2], silu_f(a0[3]) * b0[3]);
;                 w.z = cvt_pk_bf16(silu_f(a1[0]) * b1[0], silu_f(a1[1]) * b1[1]); w.w = cvt_pk_bf16(silu_f(a1[2]) * b1[2], silu_f(a1[3]) * b1[3]);
;                 *(u32x4*)(H + (size_t)(row0 + ai * 128 + m * 16) * DFF + hc0) = w;
;             }
	v_mul_f32_e32 v105, v110, v108
	v_mul_f32_e32 v108, 0xbfb8aa3b, v100
	v_mul_f32_e32 v105, v105, v106
	v_mul_f32_e32 v106, v111, v109
	v_exp_f32_e32 v108, v108
	v_mul_f32_e32 v109, 0xbfb8aa3b, v101
	v_exp_f32_e32 v109, v109
	v_mul_f32_e32 v106, v106, v107
	v_add_f32_e32 v107, 1.0, v108
	v_rcp_f32_e32 v107, v107
	v_add_f32_e32 v108, 1.0, v109
	v_rcp_f32_e32 v108, v108
	v_cvt_pk_bf16_f32 v105, v105, v106
	v_mul_f32_e32 v100, v100, v107
	v_mul_f32_e32 v96, v100, v96
	v_mul_f32_e32 v100, v101, v108
	v_mul_f32_e32 v101, 0xbfb8aa3b, v102
	v_exp_f32_e32 v101, v101
	v_mul_f32_e32 v106, 0xbfb8aa3b, v103
	v_exp_f32_e32 v106, v106
	v_mul_f32_e32 v97, v100, v97
	v_add_f32_e32 v100, 1.0, v101
	v_rcp_f32_e32 v100, v100
	v_add_f32_e32 v101, 1.0, v106
	v_rcp_f32_e32 v101, v101
	v_cvt_pk_bf16_f32 v106, v96, v97
	v_mul_f32_e32 v96, v102, v100
	v_mul_f32_e32 v96, v96, v98
	v_mul_f32_e32 v97, v103, v101
	v_mul_f32_e32 v98, 0xbfb8aa3b, v92
	v_mul_f32_e32 v97, v97, v99
	v_exp_f32_e32 v98, v98
	v_mul_f32_e32 v99, 0xbfb8aa3b, v93
	v_exp_f32_e32 v99, v99
	v_cvt_pk_bf16_f32 v107, v96, v97
	v_add_f32_e32 v98, 1.0, v98
	v_rcp_f32_e32 v98, v98
	v_add_f32_e32 v99, 1.0, v99
	v_rcp_f32_e32 v99, v99
	v_add_u32_e32 v96, 16, v150
	v_mad_i64_i32 v[96:97], s[16:17], v96, s40, v[112:113]
	v_mul_f32_e32 v92, v92, v98
	v_lshl_add_u64 v[96:97], v[96:97], 0, v[114:115]
	v_mul_f32_e32 v88, v92, v88
	v_mul_f32_e32 v92, v93, v99
	v_mul_f32_e32 v93, 0xbfb8aa3b, v94
	global_store_dwordx4 v[96:97], v[104:107], off
	v_exp_f32_e32 v93, v93
	v_mul_f32_e32 v96, 0xbfb8aa3b, v95
	v_exp_f32_e32 v96, v96
	v_mul_f32_e32 v89, v92, v89
	v_add_f32_e32 v92, 1.0, v93
	v_rcp_f32_e32 v92, v92
	v_add_f32_e32 v93, 1.0, v96
	v_rcp_f32_e32 v93, v93
	v_cvt_pk_bf16_f32 v88, v88, v89
	v_mul_f32_e32 v89, v94, v92
	v_mul_f32_e32 v92, 0xbfb8aa3b, v84
	v_mul_f32_e32 v89, v89, v90
	v_mul_f32_e32 v90, v95, v93
	v_exp_f32_e32 v92, v92
	v_mul_f32_e32 v93, 0xbfb8aa3b, v85
	v_exp_f32_e32 v93, v93
	v_mul_f32_e32 v90, v90, v91
	v_add_f32_e32 v91, 1.0, v92
	v_rcp_f32_e32 v91, v91
	v_add_f32_e32 v92, 1.0, v93
	v_rcp_f32_e32 v92, v92
	v_cvt_pk_bf16_f32 v89, v89, v90
	v_mul_f32_e32 v84, v84, v91
	v_mul_f32_e32 v80, v84, v80
	v_mul_f32_e32 v84, v85, v92
	v_mul_f32_e32 v85, 0xbfb8aa3b, v86
	v_exp_f32_e32 v85, v85
	v_mul_f32_e32 v90, 0xbfb8aa3b, v87
	v_exp_f32_e32 v90, v90
	v_mul_f32_e32 v81, v84, v81
	v_add_f32_e32 v84, 1.0, v85
	v_rcp_f32_e32 v84, v84
	v_add_f32_e32 v85, 1.0, v90
	v_rcp_f32_e32 v85, v85
	v_cvt_pk_bf16_f32 v90, v80, v81
	v_mul_f32_e32 v80, v86, v84
	v_mul_f32_e32 v80, v80, v82
	v_mul_f32_e32 v81, v87, v85
	v_mul_f32_e32 v82, 0xbfb8aa3b, v76
	v_mul_f32_e32 v81, v81, v83
	v_exp_f32_e32 v82, v82
	v_mul_f32_e32 v83, 0xbfb8aa3b, v77
	v_exp_f32_e32 v83, v83
	v_cvt_pk_bf16_f32 v91, v80, v81
	v_add_f32_e32 v82, 1.0, v82
	v_rcp_f32_e32 v82, v82
	v_add_f32_e32 v83, 1.0, v83
	v_rcp_f32_e32 v83, v83
	v_add_u32_e32 v80, 32, v150
	v_mad_i64_i32 v[80:81], s[16:17], v80, s40, v[112:113]
	v_mul_f32_e32 v76, v76, v82
	v_lshl_add_u64 v[80:81], v[80:81], 0, v[114:115]
	v_mul_f32_e32 v72, v76, v72
	v_mul_f32_e32 v76, v77, v83
	v_mul_f32_e32 v77, 0xbfb8aa3b, v78
	global_store_dwordx4 v[80:81], v[88:91], off
	v_exp_f32_e32 v77, v77
	v_mul_f32_e32 v80, 0xbfb8aa3b, v79
	v_exp_f32_e32 v80, v80
	v_mul_f32_e32 v73, v76, v73
	v_add_f32_e32 v76, 1.0, v77
	v_rcp_f32_e32 v76, v76
	v_add_f32_e32 v77, 1.0, v80
	v_rcp_f32_e32 v77, v77
	v_cvt_pk_bf16_f32 v72, v72, v73
	v_mul_f32_e32 v73, v78, v76
	v_mul_f32_e32 v76, 0xbfb8aa3b, v68
	v_mul_f32_e32 v73, v73, v74
	v_mul_f32_e32 v74, v79, v77
	v_exp_f32_e32 v76, v76
	v_mul_f32_e32 v77, 0xbfb8aa3b, v69
	v_exp_f32_e32 v77, v77
	v_mul_f32_e32 v74, v74, v75
	v_add_f32_e32 v75, 1.0, v76
	v_rcp_f32_e32 v75, v75
	v_add_f32_e32 v76, 1.0, v77
	v_rcp_f32_e32 v76, v76
	v_cvt_pk_bf16_f32 v73, v73, v74
	v_mul_f32_e32 v68, v68, v75
	v_mul_f32_e32 v64, v68, v64
	v_mul_f32_e32 v68, v69, v76
	v_mul_f32_e32 v69, 0xbfb8aa3b, v70
	v_exp_f32_e32 v69, v69
	v_mul_f32_e32 v74, 0xbfb8aa3b, v71
	v_exp_f32_e32 v74, v74
	v_mul_f32_e32 v65, v68, v65
	v_add_f32_e32 v68, 1.0, v69
	v_rcp_f32_e32 v68, v68
	v_add_f32_e32 v69, 1.0, v74
	v_rcp_f32_e32 v69, v69
	v_cvt_pk_bf16_f32 v74, v64, v65
	v_mul_f32_e32 v64, v70, v68
	v_mul_f32_e32 v64, v64, v66
	v_mul_f32_e32 v65, v71, v69
	v_mul_f32_e32 v66, 0xbfb8aa3b, v60
	v_mul_f32_e32 v65, v65, v67
	v_exp_f32_e32 v66, v66
	v_mul_f32_e32 v67, 0xbfb8aa3b, v61
	v_cvt_pk_bf16_f32 v75, v64, v65
	v_add_u32_e32 v64, 48, v150
	v_exp_f32_e32 v67, v67
	v_mad_i64_i32 v[64:65], s[16:17], v64, s40, v[112:113]
	v_lshl_add_u64 v[64:65], v[64:65], 0, v[114:115]
	global_store_dwordx4 v[64:65], v[72:75], off
	v_add_f32_e32 v64, 1.0, v66
	v_rcp_f32_e32 v64, v64
	v_add_f32_e32 v65, 1.0, v67
	v_rcp_f32_e32 v65, v65
	v_add_u32_e32 v66, 0x80, v150
	v_mul_f32_e32 v60, v60, v64
	v_mul_f32_e32 v52, v60, v52
	v_mul_f32_e32 v60, v61, v65
	v_mul_f32_e32 v61, 0xbfb8aa3b, v62
	v_exp_f32_e32 v61, v61
	v_mul_f32_e32 v64, 0xbfb8aa3b, v63
	v_exp_f32_e32 v64, v64
	v_mul_f32_e32 v53, v60, v53
	v_add_f32_e32 v60, 1.0, v61
	v_rcp_f32_e32 v60, v60
	v_add_f32_e32 v61, 1.0, v64
	v_rcp_f32_e32 v61, v61
	v_cvt_pk_bf16_f32 v52, v52, v53
	v_mul_f32_e32 v53, v62, v60
	v_mul_f32_e32 v60, 0xbfb8aa3b, v56
	v_exp_f32_e32 v60, v60
	v_mul_f32_e32 v53, v53, v54
	v_mul_f32_e32 v54, v63, v61
	v_mul_f32_e32 v61, 0xbfb8aa3b, v57
	v_exp_f32_e32 v61, v61
	v_mul_f32_e32 v54, v54, v55
	v_add_f32_e32 v55, 1.0, v60
	v_rcp_f32_e32 v55, v55
	v_add_f32_e32 v60, 1.0, v61
	v_rcp_f32_e32 v60, v60
	v_cvt_pk_bf16_f32 v53, v53, v54
	v_mul_f32_e32 v54, v56, v55
	v_mul_f32_e32 v55, 0xbfb8aa3b, v58
	v_exp_f32_e32 v55, v55
	v_mul_f32_e32 v56, 0xbfb8aa3b, v59
; __device__ __forceinline__ unsigned cvt_pk_bf16(float lo, float hi) { unsigned r; asm volatile("v_cvt_pk_bf16_f32 %0, %1, %2" : "=v"(r) : "v"(lo), "v"(hi)); return r; }
; __device__ __forceinline__ float silu_f(float a) { return a * __builtin_amdgcn_rcpf(1.0f + __expf(-a)); }
; template <class Epi, class Sched>
; __device__ __forceinline__ void gemm_phase(LAS unsigned char* lds, const Gemm g, const Sched& S, const Epi& E) {
;     ...
;         E(acc, cur, wr, wc, fr, fq);
;         if (!has_next) break;
;     __device__ __forceinline__ void operator()(const AccT& acc, const Unit& u, int wr, int wc, int fr, int fq) const {
;     ...
;         const int row0 = u.pm * 256 + wr * 64 + fr, hc0 = u.pn * 128 + wc * 32 + 8 * fq;
; #pragma unroll
;         for (int ai = 0; ai < 2; ++ai)
; #pragma unroll
;             for (int m = 0; m < 4; ++m) {
;                 const f32x4 a0 = acc[ai][0][m][0], a1 = acc[ai][0][m][1], b0 = acc[ai][1][m][0], b1 = acc[ai][1][m][1];
;                 u32x4 w;
;                 w.x = cvt_pk_bf16(silu_f(a0[0]) * b0[0], silu_f(a0[1]) * b0[1]); w.y = cvt_pk_bf16(silu_f(a0[2]) * b0[2], silu_f(a0[3]) * b0[3]);
;                 w.z = cvt_pk_bf16(silu_f(a1[0]) * b1[0], silu_f(a1[1]) * b1[1]); w.w = cvt_pk_bf16(silu_f(a1[2]) * b1[2], silu_f(a1[3]) * b1[3]);
;                 *(u32x4*)(H + (size_t)(row0 + ai * 128 + m * 16) * DFF + hc0) = w;
;             }
	v_exp_f32_e32 v56, v56
	v_mul_f32_e32 v48, v54, v48
	v_mul_f32_e32 v54, v57, v60
	v_mul_f32_e32 v49, v54, v49
	v_add_f32_e32 v54, 1.0, v55
	v_rcp_f32_e32 v55, v54
	v_add_f32_e32 v54, 1.0, v56
	v_rcp_f32_e32 v56, v54
	v_cvt_pk_bf16_f32 v54, v48, v49
	v_mul_f32_e32 v48, v58, v55
	v_mul_f32_e32 v48, v48, v50
	v_mul_f32_e32 v49, v59, v56
	v_mul_f32_e32 v50, 0xbfb8aa3b, v44
	v_mul_f32_e32 v49, v49, v51
	v_exp_f32_e32 v50, v50
	v_mul_f32_e32 v51, 0xbfb8aa3b, v45
	v_exp_f32_e32 v51, v51
	v_cvt_pk_bf16_f32 v55, v48, v49
	v_add_f32_e32 v50, 1.0, v50
	v_rcp_f32_e32 v50, v50
	v_add_f32_e32 v51, 1.0, v51
	v_rcp_f32_e32 v51, v51
	v_mad_i64_i32 v[48:49], s[16:17], v66, s40, v[112:113]
	v_mul_f32_e32 v44, v44, v50
	v_mul_f32_e32 v36, v44, v36
	v_mul_f32_e32 v44, v45, v51
	v_mul_f32_e32 v45, 0xbfb8aa3b, v46
	v_exp_f32_e32 v45, v45
	v_lshl_add_u64 v[48:49], v[48:49], 0, v[114:115]
	global_store_dwordx4 v[48:49], v[52:55], off
	v_mul_f32_e32 v48, 0xbfb8aa3b, v47
	v_exp_f32_e32 v48, v48
	v_mul_f32_e32 v37, v44, v37
	v_add_f32_e32 v44, 1.0, v45
	v_rcp_f32_e32 v44, v44
	v_add_f32_e32 v45, 1.0, v48
	v_rcp_f32_e32 v45, v45
	v_cvt_pk_bf16_f32 v36, v36, v37
	v_mul_f32_e32 v37, v46, v44
	v_mul_f32_e32 v44, 0xbfb8aa3b, v40
	v_exp_f32_e32 v44, v44
	v_mul_f32_e32 v37, v37, v38
	v_mul_f32_e32 v38, v47, v45
	v_mul_f32_e32 v45, 0xbfb8aa3b, v41
	v_exp_f32_e32 v45, v45
	v_mul_f32_e32 v38, v38, v39
	v_add_f32_e32 v39, 1.0, v44
	v_rcp_f32_e32 v39, v39
	v_add_f32_e32 v44, 1.0, v45
	v_rcp_f32_e32 v44, v44
	v_cvt_pk_bf16_f32 v37, v37, v38
	v_mul_f32_e32 v38, v40, v39
	v_mul_f32_e32 v39, 0xbfb8aa3b, v42
	v_exp_f32_e32 v39, v39
	v_mul_f32_e32 v40, 0xbfb8aa3b, v43
	v_exp_f32_e32 v40, v40
	v_mul_f32_e32 v32, v38, v32
	v_mul_f32_e32 v38, v41, v44
	v_mul_f32_e32 v33, v38, v33
	v_add_f32_e32 v38, 1.0, v39
	v_rcp_f32_e32 v39, v38
	v_add_f32_e32 v38, 1.0, v40
	v_rcp_f32_e32 v40, v38
	v_cvt_pk_bf16_f32 v38, v32, v33
	v_mul_f32_e32 v32, v42, v39
	v_mul_f32_e32 v32, v32, v34
	v_mul_f32_e32 v33, v43, v40
	v_mul_f32_e32 v34, 0xbfb8aa3b, v28
	v_mul_f32_e32 v33, v33, v35
	v_exp_f32_e32 v34, v34
	v_mul_f32_e32 v35, 0xbfb8aa3b, v29
	v_exp_f32_e32 v35, v35
	v_cvt_pk_bf16_f32 v39, v32, v33
	v_add_f32_e32 v34, 1.0, v34
	v_rcp_f32_e32 v34, v34
	v_add_f32_e32 v35, 1.0, v35
	v_rcp_f32_e32 v35, v35
	v_add_u32_e32 v32, 0x90, v150
	v_mul_f32_e32 v28, v28, v34
	v_mul_f32_e32 v20, v28, v20
	v_mul_f32_e32 v28, v29, v35
	v_mul_f32_e32 v29, 0xbfb8aa3b, v30
	v_exp_f32_e32 v29, v29
	v_mad_i64_i32 v[32:33], s[16:17], v32, s40, v[112:113]
	v_lshl_add_u64 v[32:33], v[32:33], 0, v[114:115]
	global_store_dwordx4 v[32:33], v[36:39], off
	v_mul_f32_e32 v32, 0xbfb8aa3b, v31
	v_exp_f32_e32 v32, v32
	v_mul_f32_e32 v21, v28, v21
	v_add_f32_e32 v28, 1.0, v29
	v_rcp_f32_e32 v28, v28
	v_add_f32_e32 v29, 1.0, v32
	v_rcp_f32_e32 v29, v29
	v_cvt_pk_bf16_f32 v20, v20, v21
	v_mul_f32_e32 v21, v30, v28
	v_mul_f32_e32 v28, 0xbfb8aa3b, v24
	v_exp_f32_e32 v28, v28
	v_mul_f32_e32 v21, v21, v22
	v_mul_f32_e32 v22, v31, v29
	v_mul_f32_e32 v29, 0xbfb8aa3b, v25
	v_exp_f32_e32 v29, v29
	v_mul_f32_e32 v22, v22, v23
	v_add_f32_e32 v23, 1.0, v28
	v_rcp_f32_e32 v23, v23
	v_add_f32_e32 v28, 1.0, v29
	v_rcp_f32_e32 v28, v28
	v_cvt_pk_bf16_f32 v21, v21, v22
	v_mul_f32_e32 v22, v24, v23
	v_mul_f32_e32 v23, 0xbfb8aa3b, v26
	v_exp_f32_e32 v23, v23
	v_mul_f32_e32 v24, 0xbfb8aa3b, v27
	v_exp_f32_e32 v24, v24
	v_mul_f32_e32 v16, v22, v16
	v_mul_f32_e32 v22, v25, v28
	v_mul_f32_e32 v17, v22, v17
	v_add_f32_e32 v22, 1.0, v23
	v_rcp_f32_e32 v23, v22
	v_add_f32_e32 v22, 1.0, v24
	v_rcp_f32_e32 v24, v22
	v_cvt_pk_bf16_f32 v22, v16, v17
	v_mul_f32_e32 v16, v26, v23
	v_mul_f32_e32 v16, v16, v18
	v_mul_f32_e32 v17, v27, v24
	v_mul_f32_e32 v18, 0xbfb8aa3b, v12
	v_mul_f32_e32 v17, v17, v19
	v_exp_f32_e32 v18, v18
	v_mul_f32_e32 v19, 0xbfb8aa3b, v13
	v_exp_f32_e32 v19, v19
	v_cvt_pk_bf16_f32 v23, v16, v17
	v_add_f32_e32 v18, 1.0, v18
	v_rcp_f32_e32 v18, v18
	v_add_f32_e32 v19, 1.0, v19
	v_rcp_f32_e32 v19, v19
	v_add_u32_e32 v16, 0xa0, v150
	v_mul_f32_e32 v12, v12, v18
	v_mul_f32_e32 v4, v12, v4
	v_mul_f32_e32 v12, v13, v19
	v_mul_f32_e32 v13, 0xbfb8aa3b, v14
	v_exp_f32_e32 v13, v13
	v_mad_i64_i32 v[16:17], s[16:17], v16, s40, v[112:113]
	v_lshl_add_u64 v[16:17], v[16:17], 0, v[114:115]
	global_store_dwordx4 v[16:17], v[20:23], off
	v_mul_f32_e32 v16, 0xbfb8aa3b, v15
	v_exp_f32_e32 v16, v16
	v_mul_f32_e32 v5, v12, v5
	v_add_f32_e32 v12, 1.0, v13
	v_rcp_f32_e32 v12, v12
	v_add_f32_e32 v13, 1.0, v16
	v_rcp_f32_e32 v13, v13
	v_cvt_pk_bf16_f32 v4, v4, v5
	v_mul_f32_e32 v5, v14, v12
	v_mul_f32_e32 v12, 0xbfb8aa3b, v8
	v_exp_f32_e32 v12, v12
	v_mul_f32_e32 v5, v5, v6
	v_mul_f32_e32 v6, v15, v13
	v_mul_f32_e32 v13, 0xbfb8aa3b, v9
	v_exp_f32_e32 v13, v13
	v_mul_f32_e32 v6, v6, v7
	v_add_f32_e32 v7, 1.0, v12
	v_rcp_f32_e32 v7, v7
	v_add_f32_e32 v12, 1.0, v13
	v_rcp_f32_e32 v12, v12
	v_cvt_pk_bf16_f32 v5, v5, v6
	v_mul_f32_e32 v6, v8, v7
	v_mul_f32_e32 v7, 0xbfb8aa3b, v10
	v_exp_f32_e32 v7, v7
	v_mul_f32_e32 v8, 0xbfb8aa3b, v11
	v_exp_f32_e32 v8, v8
	v_mul_f32_e32 v0, v6, v0
	v_mul_f32_e32 v6, v9, v12
	v_mul_f32_e32 v1, v6, v1
	v_add_f32_e32 v6, 1.0, v7
	v_rcp_f32_e32 v7, v6
	v_add_f32_e32 v6, 1.0, v8
	v_rcp_f32_e32 v8, v6
	v_cvt_pk_bf16_f32 v6, v0, v1
	v_mul_f32_e32 v0, v10, v7
	v_mul_f32_e32 v0, v0, v2
	v_mul_f32_e32 v1, v11, v8
	v_mul_f32_e32 v1, v1, v3
	v_cvt_pk_bf16_f32 v7, v0, v1
	v_add_u32_e32 v0, 0xb0, v150
	v_mad_i64_i32 v[0:1], s[16:17], v0, s40, v[112:113]
	v_lshl_add_u64 v[0:1], v[0:1], 0, v[114:115]
	s_and_b64 vcc, exec, s[2:3]
	s_mov_b32 s41, s4
	s_mov_b32 s14, s6
	s_mov_b64 s[18:19], s[12:13]
	s_mov_b64 s[16:17], s[10:11]
	global_store_dwordx4 v[0:1], v[4:7], off
	s_cbranch_vccz .LBB0_1018
	s_branch .Lconc_end_g11
; __device__ __forceinline__ unsigned cvt_pk_bf16(float lo, float hi) { unsigned r; asm volatile("v_cvt_pk_bf16_f32 %0, %1, %2" : "=v"(r) : "v"(lo), "v"(hi)); return r; }
; __device__ __forceinline__ float silu_f(float a) { return a * __builtin_amdgcn_rcpf(1.0f + __expf(-a)); }
;     __device__ __forceinline__ void operator()(const AccT& acc, const Unit& u, int wr, int wc, int fr, int fq) const {
;         asm volatile("" : "+v"(fr), "+v"(fq));
;         const int row0 = u.pm * 256 + wr * 64 + fr, hc0 = u.pn * 128 + wc * 32 + 8 * fq;
; #pragma unroll
;         for (int ai = 0; ai < 2; ++ai)
; #pragma unroll
;             for (int m = 0; m < 4; ++m) {
;                 const f32x4 a0 = acc[ai][0][m][0], a1 = acc[ai][0][m][1], b0 = acc[ai][1][m][0], b1 = acc[ai][1][m][1];
;                 u32x4 w;
;                 w.x = cvt_pk_bf16(silu_f(a0[0]) * b0[0], silu_f(a0[1]) * b0[1]); w.y = cvt_pk_bf16(silu_f(a0[2]) * b0[2], silu_f(a0[3]) * b0[3]);
;                 w.z = cvt_pk_bf16(silu_f(a1[0]) * b1[0], silu_f(a1[1]) * b1[1]); w.w = cvt_pk_bf16(silu_f(a1[2]) * b1[2], silu_f(a1[3]) * b1[3]);
;                 *(u32x4*)(H + (size_t)(row0 + ai * 128 + m * 16) * DFF + hc0) = w;
.Lconc_epi1_g11:
	v_mul_f32_e32 v152, 0xbfb8aa3b, v124
	v_mov_b32_e32 v150, v144
	v_mov_b32_e32 v151, v145
	s_lshl_b32 s5, s14, 8
	v_exp_f32_e32 v153, v152
	v_mul_f32_e32 v152, 0xbfb8aa3b, v125
	s_add_i32 s5, s5, s33
	v_exp_f32_e32 v154, v152
	v_add_u32_e32 v150, s5, v150
	s_lshl_b32 s5, s41, 7
	s_or_b32 s5, s5, s34
	v_lshl_add_u32 v152, v151, 3, s5
	v_add_f32_e32 v151, 1.0, v153
	v_rcp_f32_e32 v151, v151
	v_add_f32_e32 v153, 1.0, v154
	v_rcp_f32_e32 v154, v153
	v_ashrrev_i32_e32 v153, 31, v152
	v_mul_f32_e32 v124, v124, v151
	v_mul_f32_e32 v120, v124, v120
	v_mul_f32_e32 v124, v125, v154
	v_mul_f32_e32 v125, 0xbfb8aa3b, v126
	v_exp_f32_e32 v125, v125
	v_mul_f32_e32 v151, 0xbfb8aa3b, v127
	v_exp_f32_e32 v151, v151
	v_mul_f32_e32 v121, v124, v121
	v_add_f32_e32 v124, 1.0, v125
	v_rcp_f32_e32 v124, v124
	v_add_f32_e32 v125, 1.0, v151
	v_rcp_f32_e32 v125, v125
	v_cvt_pk_bf16_f32 v120, v120, v121
	v_mul_f32_e32 v121, v126, v124
	v_mul_f32_e32 v124, 0xbfb8aa3b, v116
	v_mul_f32_e32 v121, v121, v122
	v_mul_f32_e32 v122, v127, v125
	v_exp_f32_e32 v124, v124
	v_mul_f32_e32 v125, 0xbfb8aa3b, v117
	v_exp_f32_e32 v125, v125
	v_mul_f32_e32 v122, v122, v123
	v_add_f32_e32 v123, 1.0, v124
	v_rcp_f32_e32 v123, v123
	v_add_f32_e32 v124, 1.0, v125
	v_rcp_f32_e32 v124, v124
	v_cvt_pk_bf16_f32 v121, v121, v122
	v_mul_f32_e32 v116, v116, v123
	v_mul_f32_e32 v112, v116, v112
	v_mul_f32_e32 v116, v117, v124
	v_mul_f32_e32 v117, 0xbfb8aa3b, v118
	v_exp_f32_e32 v117, v117
	v_mul_f32_e32 v122, 0xbfb8aa3b, v119
	v_exp_f32_e32 v122, v122
	v_mul_f32_e32 v113, v116, v113
	v_add_f32_e32 v116, 1.0, v117
	v_rcp_f32_e32 v116, v116
	v_add_f32_e32 v117, 1.0, v122
	v_rcp_f32_e32 v117, v117
	v_cvt_pk_bf16_f32 v122, v112, v113
	v_mul_f32_e32 v112, v118, v116
	v_mul_f32_e32 v118, 0xbfb8aa3b, v108
	v_mul_f32_e32 v113, v119, v117
	v_exp_f32_e32 v118, v118
	v_mul_f32_e32 v119, 0xbfb8aa3b, v109
	v_exp_f32_e32 v119, v119
	v_mul_f32_e32 v112, v112, v114
	v_add_f32_e32 v118, 1.0, v118
	v_rcp_f32_e32 v118, v118
	v_add_f32_e32 v119, 1.0, v119
	v_rcp_f32_e32 v119, v119
	v_mul_f32_e32 v113, v113, v115
	v_cvt_pk_bf16_f32 v123, v112, v113
	v_mov_b64_e32 v[112:113], s[82:83]
	v_mad_i64_i32 v[116:117], s[16:17], v150, s40, v[112:113]
	v_lshlrev_b64 v[114:115], 1, v[152:153]
	v_mul_f32_e32 v108, v108, v118
	v_lshl_add_u64 v[116:117], v[116:117], 0, v[114:115]
	v_mul_f32_e32 v104, v108, v104
	v_mul_f32_e32 v108, v109, v119
	v_mul_f32_e32 v109, 0xbfb8aa3b, v110
	global_store_dwordx4 v[116:117], v[120:123], off
	v_exp_f32_e32 v109, v109
	v_mul_f32_e32 v116, 0xbfb8aa3b, v111
	v_exp_f32_e32 v116, v116
	v_mul_f32_e32 v105, v108, v105
	v_add_f32_e32 v108, 1.0, v109
	v_rcp_f32_e32 v108, v108
	v_add_f32_e32 v109, 1.0, v116
	v_rcp_f32_e32 v109, v109
	v_cvt_pk_bf16_f32 v104, v104, v105
	v_mul_f32_e32 v105, v110, v108
	v_mul_f32_e32 v108, 0xbfb8aa3b, v100
	v_mul_f32_e32 v105, v105, v106
	v_mul_f32_e32 v106, v111, v109
	v_exp_f32_e32 v108, v108
	v_mul_f32_e32 v109, 0xbfb8aa3b, v101
	v_exp_f32_e32 v109, v109
	v_mul_f32_e32 v106, v106, v107
	v_add_f32_e32 v107, 1.0, v108
	v_rcp_f32_e32 v107, v107
	v_add_f32_e32 v108, 1.0, v109
	v_rcp_f32_e32 v108, v108
	v_cvt_pk_bf16_f32 v105, v105, v106
	v_mul_f32_e32 v100, v100, v107
	v_mul_f32_e32 v96, v100, v96
	v_mul_f32_e32 v100, v101, v108
	v_mul_f32_e32 v101, 0xbfb8aa3b, v102
	v_exp_f32_e32 v101, v101
	v_mul_f32_e32 v106, 0xbfb8aa3b, v103
	v_exp_f32_e32 v106, v106
	v_mul_f32_e32 v97, v100, v97
	v_add_f32_e32 v100, 1.0, v101
	v_rcp_f32_e32 v100, v100
	v_add_f32_e32 v101, 1.0, v106
	v_rcp_f32_e32 v101, v101
	v_cvt_pk_bf16_f32 v106, v96, v97
	v_mul_f32_e32 v96, v102, v100
	v_mul_f32_e32 v96, v96, v98
	v_mul_f32_e32 v97, v103, v101
	v_mul_f32_e32 v98, 0xbfb8aa3b, v92
	v_mul_f32_e32 v97, v97, v99
	v_exp_f32_e32 v98, v98
	v_mul_f32_e32 v99, 0xbfb8aa3b, v93
	v_exp_f32_e32 v99, v99
	v_cvt_pk_bf16_f32 v107, v96, v97
	v_add_f32_e32 v98, 1.0, v98
	v_rcp_f32_e32 v98, v98
	v_add_f32_e32 v99, 1.0, v99
	v_rcp_f32_e32 v99, v99
	v_add_u32_e32 v96, 16, v150
	v_mad_i64_i32 v[96:97], s[16:17], v96, s40, v[112:113]
	v_mul_f32_e32 v92, v92, v98
	v_lshl_add_u64 v[96:97], v[96:97], 0, v[114:115]
	v_mul_f32_e32 v88, v92, v88
	v_mul_f32_e32 v92, v93, v99
	v_mul_f32_e32 v93, 0xbfb8aa3b, v94
	global_store_dwordx4 v[96:97], v[104:107], off
	v_exp_f32_e32 v93, v93
	v_mul_f32_e32 v96, 0xbfb8aa3b, v95
	v_exp_f32_e32 v96, v96
	v_mul_f32_e32 v89, v92, v89
	v_add_f32_e32 v92, 1.0, v93
	v_rcp_f32_e32 v92, v92
	v_add_f32_e32 v93, 1.0, v96
	v_rcp_f32_e32 v93, v93
	v_cvt_pk_bf16_f32 v88, v88, v89
	v_mul_f32_e32 v89, v94, v92
	v_mul_f32_e32 v92, 0xbfb8aa3b, v84
	v_mul_f32_e32 v89, v89, v90
	v_mul_f32_e32 v90, v95, v93
	v_exp_f32_e32 v92, v92
	v_mul_f32_e32 v93, 0xbfb8aa3b, v85
	v_exp_f32_e32 v93, v93
	v_mul_f32_e32 v90, v90, v91
	v_add_f32_e32 v91, 1.0, v92
	v_rcp_f32_e32 v91, v91
	v_add_f32_e32 v92, 1.0, v93
	v_rcp_f32_e32 v92, v92
	v_cvt_pk_bf16_f32 v89, v89, v90
	v_mul_f32_e32 v84, v84, v91
	v_mul_f32_e32 v80, v84, v80
	v_mul_f32_e32 v84, v85, v92
	v_mul_f32_e32 v85, 0xbfb8aa3b, v86
	v_exp_f32_e32 v85, v85
	v_mul_f32_e32 v90, 0xbfb8aa3b, v87
	v_exp_f32_e32 v90, v90
	v_mul_f32_e32 v81, v84, v81
	v_add_f32_e32 v84, 1.0, v85
	v_rcp_f32_e32 v84, v84
	v_add_f32_e32 v85, 1.0, v90
	v_rcp_f32_e32 v85, v85
	v_cvt_pk_bf16_f32 v90, v80, v81
	v_mul_f32_e32 v80, v86, v84
	v_mul_f32_e32 v80, v80, v82
	v_mul_f32_e32 v81, v87, v85
	v_mul_f32_e32 v82, 0xbfb8aa3b, v76
	v_mul_f32_e32 v81, v81, v83
	v_exp_f32_e32 v82, v82
	v_mul_f32_e32 v83, 0xbfb8aa3b, v77
	v_exp_f32_e32 v83, v83
	v_cvt_pk_bf16_f32 v91, v80, v81
	v_add_f32_e32 v82, 1.0, v82
	v_rcp_f32_e32 v82, v82
	v_add_f32_e32 v83, 1.0, v83
	v_rcp_f32_e32 v83, v83
; __device__ __forceinline__ unsigned cvt_pk_bf16(float lo, float hi) { unsigned r; asm volatile("v_cvt_pk_bf16_f32 %0, %1, %2" : "=v"(r) : "v"(lo), "v"(hi)); return r; }
; __device__ __forceinline__ float silu_f(float a) { return a * __builtin_amdgcn_rcpf(1.0f + __expf(-a)); }
;     __device__ __forceinline__ void operator()(const AccT& acc, const Unit& u, int wr, int wc, int fr, int fq) const {
;         asm volatile("" : "+v"(fr), "+v"(fq));
;         const int row0 = u.pm * 256 + wr * 64 + fr, hc0 = u.pn * 128 + wc * 32 + 8 * fq;
; #pragma unroll
;         for (int ai = 0; ai < 2; ++ai)
; #pragma unroll
;             for (int m = 0; m < 4; ++m) {
;                 const f32x4 a0 = acc[ai][0][m][0], a1 = acc[ai][0][m][1], b0 = acc[ai][1][m][0], b1 = acc[ai][1][m][1];
;                 u32x4 w;
;                 w.x = cvt_pk_bf16(silu_f(a0[0]) * b0[0], silu_f(a0[1]) * b0[1]); w.y = cvt_pk_bf16(silu_f(a0[2]) * b0[2], silu_f(a0[3]) * b0[3]);
;                 w.z = cvt_pk_bf16(silu_f(a1[0]) * b1[0], silu_f(a1[1]) * b1[1]); w.w = cvt_pk_bf16(silu_f(a1[2]) * b1[2], silu_f(a1[3]) * b1[3]);
;                 *(u32x4*)(H + (size_t)(row0 + ai * 128 + m * 16) * DFF + hc0) = w;
	v_add_u32_e32 v80, 32, v150
	v_mad_i64_i32 v[80:81], s[16:17], v80, s40, v[112:113]
	v_mul_f32_e32 v76, v76, v82
	v_lshl_add_u64 v[80:81], v[80:81], 0, v[114:115]
	v_mul_f32_e32 v72, v76, v72
	v_mul_f32_e32 v76, v77, v83
	v_mul_f32_e32 v77, 0xbfb8aa3b, v78
	global_store_dwordx4 v[80:81], v[88:91], off
	v_exp_f32_e32 v77, v77
	v_mul_f32_e32 v80, 0xbfb8aa3b, v79
	v_exp_f32_e32 v80, v80
	v_mul_f32_e32 v73, v76, v73
	v_add_f32_e32 v76, 1.0, v77
	v_rcp_f32_e32 v76, v76
	v_add_f32_e32 v77, 1.0, v80
	v_rcp_f32_e32 v77, v77
	v_cvt_pk_bf16_f32 v72, v72, v73
	v_mul_f32_e32 v73, v78, v76
	v_mul_f32_e32 v76, 0xbfb8aa3b, v68
	v_mul_f32_e32 v73, v73, v74
	v_mul_f32_e32 v74, v79, v77
	v_exp_f32_e32 v76, v76
	v_mul_f32_e32 v77, 0xbfb8aa3b, v69
	v_exp_f32_e32 v77, v77
	v_mul_f32_e32 v74, v74, v75
	v_add_f32_e32 v75, 1.0, v76
	v_rcp_f32_e32 v75, v75
	v_add_f32_e32 v76, 1.0, v77
	v_rcp_f32_e32 v76, v76
	v_cvt_pk_bf16_f32 v73, v73, v74
	v_mul_f32_e32 v68, v68, v75
	v_mul_f32_e32 v64, v68, v64
	v_mul_f32_e32 v68, v69, v76
	v_mul_f32_e32 v69, 0xbfb8aa3b, v70
	v_exp_f32_e32 v69, v69
	v_mul_f32_e32 v74, 0xbfb8aa3b, v71
	v_exp_f32_e32 v74, v74
	v_mul_f32_e32 v65, v68, v65
	v_add_f32_e32 v68, 1.0, v69
	v_rcp_f32_e32 v68, v68
	v_add_f32_e32 v69, 1.0, v74
	v_rcp_f32_e32 v69, v69
	v_cvt_pk_bf16_f32 v74, v64, v65
	v_mul_f32_e32 v64, v70, v68
	v_mul_f32_e32 v64, v64, v66
	v_mul_f32_e32 v65, v71, v69
	v_mul_f32_e32 v66, 0xbfb8aa3b, v60
	v_mul_f32_e32 v65, v65, v67
	v_exp_f32_e32 v66, v66
	v_mul_f32_e32 v67, 0xbfb8aa3b, v61
	v_cvt_pk_bf16_f32 v75, v64, v65
	v_add_u32_e32 v64, 48, v150
	v_exp_f32_e32 v67, v67
	v_mad_i64_i32 v[64:65], s[16:17], v64, s40, v[112:113]
	v_lshl_add_u64 v[64:65], v[64:65], 0, v[114:115]
	global_store_dwordx4 v[64:65], v[72:75], off
	v_add_f32_e32 v64, 1.0, v66
	v_rcp_f32_e32 v64, v64
	v_add_f32_e32 v65, 1.0, v67
	v_rcp_f32_e32 v65, v65
	v_add_u32_e32 v66, 0x80, v150
	v_mul_f32_e32 v60, v60, v64
	v_mul_f32_e32 v52, v60, v52
	v_mul_f32_e32 v60, v61, v65
	v_mul_f32_e32 v61, 0xbfb8aa3b, v62
	v_exp_f32_e32 v61, v61
	v_mul_f32_e32 v64, 0xbfb8aa3b, v63
	v_exp_f32_e32 v64, v64
	v_mul_f32_e32 v53, v60, v53
	v_add_f32_e32 v60, 1.0, v61
	v_rcp_f32_e32 v60, v60
	v_add_f32_e32 v61, 1.0, v64
	v_rcp_f32_e32 v61, v61
	v_cvt_pk_bf16_f32 v52, v52, v53
	v_mul_f32_e32 v53, v62, v60
	v_mul_f32_e32 v60, 0xbfb8aa3b, v56
	v_exp_f32_e32 v60, v60
	v_mul_f32_e32 v53, v53, v54
	v_mul_f32_e32 v54, v63, v61
	v_mul_f32_e32 v61, 0xbfb8aa3b, v57
	v_exp_f32_e32 v61, v61
	v_mul_f32_e32 v54, v54, v55
	v_add_f32_e32 v55, 1.0, v60
	v_rcp_f32_e32 v55, v55
	v_add_f32_e32 v60, 1.0, v61
	v_rcp_f32_e32 v60, v60
	v_cvt_pk_bf16_f32 v53, v53, v54
	v_mul_f32_e32 v54, v56, v55
	v_mul_f32_e32 v55, 0xbfb8aa3b, v58
	v_exp_f32_e32 v55, v55
	v_mul_f32_e32 v56, 0xbfb8aa3b, v59
	v_exp_f32_e32 v56, v56
	v_mul_f32_e32 v48, v54, v48
	v_mul_f32_e32 v54, v57, v60
	v_mul_f32_e32 v49, v54, v49
	v_add_f32_e32 v54, 1.0, v55
	v_rcp_f32_e32 v55, v54
	v_add_f32_e32 v54, 1.0, v56
	v_rcp_f32_e32 v56, v54
	v_cvt_pk_bf16_f32 v54, v48, v49
	v_mul_f32_e32 v48, v58, v55
	v_mul_f32_e32 v48, v48, v50
	v_mul_f32_e32 v49, v59, v56
	v_mul_f32_e32 v50, 0xbfb8aa3b, v44
	v_mul_f32_e32 v49, v49, v51
	v_exp_f32_e32 v50, v50
	v_mul_f32_e32 v51, 0xbfb8aa3b, v45
	v_exp_f32_e32 v51, v51
	v_cvt_pk_bf16_f32 v55, v48, v49
	v_add_f32_e32 v50, 1.0, v50
	v_rcp_f32_e32 v50, v50
	v_add_f32_e32 v51, 1.0, v51
	v_rcp_f32_e32 v51, v51
	v_mad_i64_i32 v[48:49], s[16:17], v66, s40, v[112:113]
	v_mul_f32_e32 v44, v44, v50
	v_mul_f32_e32 v36, v44, v36
	v_mul_f32_e32 v44, v45, v51
	v_mul_f32_e32 v45, 0xbfb8aa3b, v46
	v_exp_f32_e32 v45, v45
	v_lshl_add_u64 v[48:49], v[48:49], 0, v[114:115]
	global_store_dwordx4 v[48:49], v[52:55], off
	v_mul_f32_e32 v48, 0xbfb8aa3b, v47
	v_exp_f32_e32 v48, v48
	v_mul_f32_e32 v37, v44, v37
	v_add_f32_e32 v44, 1.0, v45
	v_rcp_f32_e32 v44, v44
	v_add_f32_e32 v45, 1.0, v48
	v_rcp_f32_e32 v45, v45
	v_cvt_pk_bf16_f32 v36, v36, v37
	v_mul_f32_e32 v37, v46, v44
	v_mul_f32_e32 v44, 0xbfb8aa3b, v40
	v_exp_f32_e32 v44, v44
	v_mul_f32_e32 v37, v37, v38
	v_mul_f32_e32 v38, v47, v45
	v_mul_f32_e32 v45, 0xbfb8aa3b, v41
	v_exp_f32_e32 v45, v45
	v_mul_f32_e32 v38, v38, v39
	v_add_f32_e32 v39, 1.0, v44
	v_rcp_f32_e32 v39, v39
	v_add_f32_e32 v44, 1.0, v45
	v_rcp_f32_e32 v44, v44
; __device__ __forceinline__ unsigned cvt_pk_bf16(float lo, float hi) { unsigned r; asm volatile("v_cvt_pk_bf16_f32 %0, %1, %2" : "=v"(r) : "v"(lo), "v"(hi)); return r; }
; __device__ __forceinline__ float silu_f(float a) { return a * __builtin_amdgcn_rcpf(1.0f + __expf(-a)); }
; #define PG8_WAIT_V(n) asm volatile("s_waitcnt vmcnt(" #n ")" ::: "memory")
; #define PG8_BAR __builtin_amdgcn_s_barrier()
; template <class Epi, class Sched>
; __device__ __forceinline__ void gemm_phase(LAS unsigned char* lds, const Gemm g, const Sched& S, const Epi& E) {
;     ...
;         E(acc, cur, wr, wc, fr, fq);
;         if (!has_next) break;
; #pragma unroll
;         for (int a = 0; a < 2; ++a)
; #pragma unroll
;             for (int b = 0; b < 2; ++b)
; #pragma unroll
;                 for (int m = 0; m < 4; ++m)
; #pragma unroll
;                     for (int n = 0; n < 2; ++n) acc[a][b][m][n] = (f32x4){0.f, 0.f, 0.f, 0.f};
;         cur = nxt; cA = nA; cB = nB; ++ui;
;     }
;     PG8_WAIT_V(0);
;     if (wr == 0) PG8_BAR;
;     PG8_BAR;
;     __device__ __forceinline__ void operator()(const AccT& acc, const Unit& u, int wr, int wc, int fr, int fq) const {
;     ...
;                 w.x = cvt_pk_bf16(silu_f(a0[0]) * b0[0], silu_f(a0[1]) * b0[1]); w.y = cvt_pk_bf16(silu_f(a0[2]) * b0[2], silu_f(a0[3]) * b0[3]);
;                 w.z = cvt_pk_bf16(silu_f(a1[0]) * b1[0], silu_f(a1[1]) * b1[1]); w.w = cvt_pk_bf16(silu_f(a1[2]) * b1[2], silu_f(a1[3]) * b1[3]);
;                 *(u32x4*)(H + (size_t)(row0 + ai * 128 + m * 16) * DFF + hc0) = w;
	v_cvt_pk_bf16_f32 v37, v37, v38
	v_mul_f32_e32 v38, v40, v39
	v_mul_f32_e32 v39, 0xbfb8aa3b, v42
	v_exp_f32_e32 v39, v39
	v_mul_f32_e32 v40, 0xbfb8aa3b, v43
	v_exp_f32_e32 v40, v40
	v_mul_f32_e32 v32, v38, v32
	v_mul_f32_e32 v38, v41, v44
	v_mul_f32_e32 v33, v38, v33
	v_add_f32_e32 v38, 1.0, v39
	v_rcp_f32_e32 v39, v38
	v_add_f32_e32 v38, 1.0, v40
	v_rcp_f32_e32 v40, v38
	v_cvt_pk_bf16_f32 v38, v32, v33
	v_mul_f32_e32 v32, v42, v39
	v_mul_f32_e32 v32, v32, v34
	v_mul_f32_e32 v33, v43, v40
	v_mul_f32_e32 v34, 0xbfb8aa3b, v28
	v_mul_f32_e32 v33, v33, v35
	v_exp_f32_e32 v34, v34
	v_mul_f32_e32 v35, 0xbfb8aa3b, v29
	v_exp_f32_e32 v35, v35
	v_cvt_pk_bf16_f32 v39, v32, v33
	v_add_f32_e32 v34, 1.0, v34
	v_rcp_f32_e32 v34, v34
	v_add_f32_e32 v35, 1.0, v35
	v_rcp_f32_e32 v35, v35
	v_add_u32_e32 v32, 0x90, v150
	v_mul_f32_e32 v28, v28, v34
	v_mul_f32_e32 v20, v28, v20
	v_mul_f32_e32 v28, v29, v35
	v_mul_f32_e32 v29, 0xbfb8aa3b, v30
	v_exp_f32_e32 v29, v29
	v_mad_i64_i32 v[32:33], s[16:17], v32, s40, v[112:113]
	v_lshl_add_u64 v[32:33], v[32:33], 0, v[114:115]
	global_store_dwordx4 v[32:33], v[36:39], off
	v_mul_f32_e32 v32, 0xbfb8aa3b, v31
	v_exp_f32_e32 v32, v32
	v_mul_f32_e32 v21, v28, v21
	v_add_f32_e32 v28, 1.0, v29
	v_rcp_f32_e32 v28, v28
	v_add_f32_e32 v29, 1.0, v32
	v_rcp_f32_e32 v29, v29
	v_cvt_pk_bf16_f32 v20, v20, v21
	v_mul_f32_e32 v21, v30, v28
	v_mul_f32_e32 v28, 0xbfb8aa3b, v24
	v_exp_f32_e32 v28, v28
	v_mul_f32_e32 v21, v21, v22
	v_mul_f32_e32 v22, v31, v29
	v_mul_f32_e32 v29, 0xbfb8aa3b, v25
	v_exp_f32_e32 v29, v29
	v_mul_f32_e32 v22, v22, v23
	v_add_f32_e32 v23, 1.0, v28
	v_rcp_f32_e32 v23, v23
	v_add_f32_e32 v28, 1.0, v29
	v_rcp_f32_e32 v28, v28
	v_cvt_pk_bf16_f32 v21, v21, v22
	v_mul_f32_e32 v22, v24, v23
	v_mul_f32_e32 v23, 0xbfb8aa3b, v26
	v_exp_f32_e32 v23, v23
	v_mul_f32_e32 v24, 0xbfb8aa3b, v27
	v_exp_f32_e32 v24, v24
	v_mul_f32_e32 v16, v22, v16
	v_mul_f32_e32 v22, v25, v28
	v_mul_f32_e32 v17, v22, v17
	v_add_f32_e32 v22, 1.0, v23
	v_rcp_f32_e32 v23, v22
	v_add_f32_e32 v22, 1.0, v24
	v_rcp_f32_e32 v24, v22
	v_cvt_pk_bf16_f32 v22, v16, v17
	v_mul_f32_e32 v16, v26, v23
	v_mul_f32_e32 v16, v16, v18
	v_mul_f32_e32 v17, v27, v24
	v_mul_f32_e32 v18, 0xbfb8aa3b, v12
	v_mul_f32_e32 v17, v17, v19
	v_exp_f32_e32 v18, v18
	v_mul_f32_e32 v19, 0xbfb8aa3b, v13
	v_exp_f32_e32 v19, v19
	v_cvt_pk_bf16_f32 v23, v16, v17
	v_add_f32_e32 v18, 1.0, v18
	v_rcp_f32_e32 v18, v18
	v_add_f32_e32 v19, 1.0, v19
	v_rcp_f32_e32 v19, v19
	v_add_u32_e32 v16, 0xa0, v150
	v_mul_f32_e32 v12, v12, v18
	v_mul_f32_e32 v4, v12, v4
	v_mul_f32_e32 v12, v13, v19
	v_mul_f32_e32 v13, 0xbfb8aa3b, v14
	v_exp_f32_e32 v13, v13
	v_mad_i64_i32 v[16:17], s[16:17], v16, s40, v[112:113]
	v_lshl_add_u64 v[16:17], v[16:17], 0, v[114:115]
	global_store_dwordx4 v[16:17], v[20:23], off
	v_mul_f32_e32 v16, 0xbfb8aa3b, v15
	v_exp_f32_e32 v16, v16
	v_mul_f32_e32 v5, v12, v5
	v_add_f32_e32 v12, 1.0, v13
	v_rcp_f32_e32 v12, v12
	v_add_f32_e32 v13, 1.0, v16
	v_rcp_f32_e32 v13, v13
	v_cvt_pk_bf16_f32 v4, v4, v5
	v_mul_f32_e32 v5, v14, v12
	v_mul_f32_e32 v12, 0xbfb8aa3b, v8
	v_exp_f32_e32 v12, v12
	v_mul_f32_e32 v5, v5, v6
	v_mul_f32_e32 v6, v15, v13
	v_mul_f32_e32 v13, 0xbfb8aa3b, v9
	v_exp_f32_e32 v13, v13
	v_mul_f32_e32 v6, v6, v7
	v_add_f32_e32 v7, 1.0, v12
	v_rcp_f32_e32 v7, v7
	v_add_f32_e32 v12, 1.0, v13
	v_rcp_f32_e32 v12, v12
	v_cvt_pk_bf16_f32 v5, v5, v6
	v_mul_f32_e32 v6, v8, v7
	v_mul_f32_e32 v7, 0xbfb8aa3b, v10
	v_exp_f32_e32 v7, v7
	v_mul_f32_e32 v8, 0xbfb8aa3b, v11
	v_exp_f32_e32 v8, v8
	v_mul_f32_e32 v0, v6, v0
	v_mul_f32_e32 v6, v9, v12
	v_mul_f32_e32 v1, v6, v1
	v_add_f32_e32 v6, 1.0, v7
	v_rcp_f32_e32 v7, v6
	v_add_f32_e32 v6, 1.0, v8
	v_rcp_f32_e32 v8, v6
	v_cvt_pk_bf16_f32 v6, v0, v1
	v_mul_f32_e32 v0, v10, v7
	v_mul_f32_e32 v0, v0, v2
	v_mul_f32_e32 v1, v11, v8
	v_mul_f32_e32 v1, v1, v3
	v_cvt_pk_bf16_f32 v7, v0, v1
	v_add_u32_e32 v0, 0xb0, v150
	v_mad_i64_i32 v[0:1], s[16:17], v0, s40, v[112:113]
	v_lshl_add_u64 v[0:1], v[0:1], 0, v[114:115]
	s_and_b64 vcc, exec, s[2:3]
	s_mov_b32 s41, s4
	s_mov_b32 s14, s6
	s_mov_b64 s[18:19], s[12:13]
	s_mov_b64 s[16:17], s[10:11]
	global_store_dwordx4 v[0:1], v[4:7], off
	s_barrier
	s_cbranch_vccz .LBB0_1018
.Lconc_end_g11:
	s_waitcnt vmcnt(0)
	s_cmpk_gt_u32 s22, 0xff
	s_cbranch_scc1 .LBB0_1025
	s_barrier
